# scan consumer: per-step y partials kept in 8 registers and reduced every 8 steps with a DPP reduce-scatter (17 ops instead of 32)
# speedup vs baseline: 1.0164x; 1.0032x over previous
; DEV void scan_tile(const Params& p, int l, int tile, char* smem) {
;     ...
;   const int r8 = lane >> 3, cg = lane & 7;
;   for (int ch = 0; ch < 136; ++ch) {
;     const int buf = ch & 1;
;     if (w < 4) {
;       const float* cb = arr + buf * 32 * 384;
;       const int vo = 320 + half * 32 + w * 8 + r8;
;       float* yw = ybuf + buf * 1024 + cg * 32 + w * 8 + r8;
;       auto ldops = [&](ScanOps& o, int sl) {
;         const f32x4* b4 = (const f32x4*)(cb + sl * 384);
;         o.nkk0 = b4[cg * 2]; o.nkk1 = b4[cg * 2 + 1];
;         o.w0 = b4[16 + cg * 2]; o.w1 = b4[16 + cg * 2 + 1];
;         o.kka0 = b4[32 + cg * 2]; o.kka1 = b4[32 + cg * 2 + 1];
;         o.kd0 = b4[48 + cg * 2]; o.kd1 = b4[48 + cg * 2 + 1];
;         o.r0 = b4[64 + cg * 2]; o.r1 = b4[64 + cg * 2 + 1];
;         o.v = cb[sl * 384 + vo];
;       };
;       float ykeep = 0.f;
;       auto step = [&](const ScanOps& o, int sl) {
;         const f32x4 sA = S0 * o.nkk0 + S1 * o.nkk1;
;         const float sa = red8((sA[0] + sA[1]) + (sA[2] + sA[3]));
;         S0 = S0 * o.w0 + (o.kka0 * sa + o.kd0 * o.v);
;         S1 = S1 * o.w1 + (o.kka1 * sa + o.kd1 * o.v);
;         const f32x4 yA = S0 * o.r0 + S1 * o.r1;
;         const float y = red8((yA[0] + yA[1]) + (yA[2] + yA[3]));
;         ykeep = (cg == (sl & 7)) ? y : ykeep;
;       };
;       ScanOps oa, ob;
;       ldops(oa, 0);
; #pragma unroll
;       for (int s8 = 0; s8 < 32; s8 += 8) {
; #pragma unroll
;         for (int q = 0; q < 8; q += 2) {
;           ldops(ob, s8 + q + 1);
;           step(oa, s8 + q);
;           ldops(oa, (s8 + q + 2) & 31);
;           step(ob, s8 + q + 1);
;         }
;         yw[s8 * 32] = ykeep;
;       }
.Lsc_consumer:
	s_lshl_b32 s58, s47, 3
	v_add_u32_e32 v122, s58, v122
	v_lshlrev_b32_e32 v117, 5, v121
	s_lshl_b32 s58, s30, 7
	v_lshl_add_u32 v118, v122, 2, s58
	v_lshlrev_b32_e32 v119, 7, v121
	v_lshl_add_u32 v119, v122, 2, v119
	v_add_u32_e32 v119, 0x18000, v119
	v_and_b32_e32 v123, 2, v121
	v_cmp_eq_u32_e64 s[62:63], 0, v123
	v_and_b32_e32 v123, 1, v121
	v_cmp_eq_u32_e64 s[64:65], 0, v123
	v_mov_b32_e32 v0, 0
	v_mov_b32_e32 v1, 0
	v_mov_b32_e32 v2, 0
	v_mov_b32_e32 v3, 0
	v_mov_b32_e32 v4, 0
	v_mov_b32_e32 v5, 0
	v_mov_b32_e32 v6, 0
	v_mov_b32_e32 v7, 0
	v_mov_b32_e32 v116, 0
	v_mov_b32_e32 v114, 0
	s_barrier
	s_barrier
.Lsc_cloop:
	ds_read_b128 v[8:11], v117 offset:0
	ds_read_b128 v[12:15], v117 offset:16
	ds_read_b128 v[16:19], v117 offset:256
	ds_read_b128 v[20:23], v117 offset:272
	ds_read_b128 v[24:27], v117 offset:512
	ds_read_b128 v[28:31], v117 offset:528
	ds_read_b128 v[32:35], v117 offset:768
	ds_read_b128 v[36:39], v117 offset:784
	ds_read_b128 v[40:43], v117 offset:1024
	ds_read_b128 v[44:47], v117 offset:1040
	ds_read2st64_b32 v[88:89], v118 offset0:5 offset1:11
	s_waitcnt lgkmcnt(0)
	ds_read_b128 v[48:51], v117 offset:1536
	ds_read_b128 v[52:55], v117 offset:1552
	ds_read_b128 v[56:59], v117 offset:1792
	ds_read_b128 v[60:63], v117 offset:1808
	ds_read_b128 v[64:67], v117 offset:2048
	ds_read_b128 v[68:71], v117 offset:2064
	ds_read_b128 v[72:75], v117 offset:2304
	ds_read_b128 v[76:79], v117 offset:2320
	ds_read_b128 v[80:83], v117 offset:2560
	ds_read_b128 v[84:87], v117 offset:2576
	v_pk_mul_f32 v[92:93], v[0:1], v[8:9]
	v_pk_mul_f32 v[94:95], v[2:3], v[10:11]
	v_pk_fma_f32 v[92:93], v[4:5], v[12:13], v[92:93]
	v_pk_fma_f32 v[94:95], v[6:7], v[14:15], v[94:95]
	v_pk_mul_f32 v[102:103], v[32:33], v[88:89] op_sel_hi:[1,0]
	v_pk_add_f32 v[92:93], v[92:93], v[94:95]
	v_pk_mul_f32 v[104:105], v[34:35], v[88:89] op_sel_hi:[1,0]
	v_add_f32_e32 v110, v92, v93
	v_pk_mul_f32 v[106:107], v[36:37], v[88:89] op_sel_hi:[1,0]
	v_pk_mul_f32 v[108:109], v[38:39], v[88:89] op_sel_hi:[1,0]
	v_add_f32_dpp v110, v110, v110 quad_perm:[1,0,3,2] row_mask:0xf bank_mask:0xf bound_ctrl:1
	v_pk_fma_f32 v[0:1], v[0:1], v[16:17], v[102:103]
	v_pk_fma_f32 v[2:3], v[2:3], v[18:19], v[104:105]
	v_add_f32_dpp v110, v110, v110 quad_perm:[2,3,0,1] row_mask:0xf bank_mask:0xf bound_ctrl:1
	v_pk_fma_f32 v[4:5], v[4:5], v[20:21], v[106:107]
	v_pk_fma_f32 v[6:7], v[6:7], v[22:23], v[108:109]
	v_add_f32_dpp v112, v110, v110 row_half_mirror row_mask:0xf bank_mask:0xf bound_ctrl:1
	v_pk_fma_f32 v[0:1], v[24:25], v[112:113], v[0:1] op_sel_hi:[1,0,1]
	v_pk_fma_f32 v[2:3], v[26:27], v[112:113], v[2:3] op_sel_hi:[1,0,1]
	v_pk_fma_f32 v[4:5], v[28:29], v[112:113], v[4:5] op_sel_hi:[1,0,1]
	v_pk_fma_f32 v[6:7], v[30:31], v[112:113], v[6:7] op_sel_hi:[1,0,1]
	v_pk_mul_f32 v[98:99], v[0:1], v[40:41]
	v_pk_mul_f32 v[100:101], v[2:3], v[42:43]
	v_pk_fma_f32 v[98:99], v[4:5], v[44:45], v[98:99]
	v_pk_fma_f32 v[100:101], v[6:7], v[46:47], v[100:101]
	v_pk_add_f32 v[98:99], v[98:99], v[100:101]
	v_add_f32_e32 v120, v98, v99
	s_waitcnt lgkmcnt(0)
	ds_read_b128 v[8:11], v117 offset:3072
	ds_read_b128 v[12:15], v117 offset:3088
	ds_read_b128 v[16:19], v117 offset:3328
	ds_read_b128 v[20:23], v117 offset:3344
	ds_read_b128 v[24:27], v117 offset:3584
	ds_read_b128 v[28:31], v117 offset:3600
	ds_read_b128 v[32:35], v117 offset:3840
	ds_read_b128 v[36:39], v117 offset:3856
	ds_read_b128 v[40:43], v117 offset:4096
	ds_read_b128 v[44:47], v117 offset:4112
	ds_read2st64_b32 v[90:91], v118 offset0:17 offset1:23
	v_pk_mul_f32 v[92:93], v[0:1], v[48:49]
	v_pk_mul_f32 v[94:95], v[2:3], v[50:51]
	v_pk_fma_f32 v[92:93], v[4:5], v[52:53], v[92:93]
	v_pk_fma_f32 v[94:95], v[6:7], v[54:55], v[94:95]
	v_pk_mul_f32 v[102:103], v[72:73], v[88:89] op_sel:[0,1] op_sel_hi:[1,1]
	v_pk_add_f32 v[92:93], v[92:93], v[94:95]
	v_pk_mul_f32 v[104:105], v[74:75], v[88:89] op_sel:[0,1] op_sel_hi:[1,1]
	v_add_f32_e32 v110, v92, v93
	v_pk_mul_f32 v[106:107], v[76:77], v[88:89] op_sel:[0,1] op_sel_hi:[1,1]
	v_pk_mul_f32 v[108:109], v[78:79], v[88:89] op_sel:[0,1] op_sel_hi:[1,1]
	v_add_f32_dpp v110, v110, v110 quad_perm:[1,0,3,2] row_mask:0xf bank_mask:0xf bound_ctrl:1
	v_pk_fma_f32 v[0:1], v[0:1], v[56:57], v[102:103]
	v_pk_fma_f32 v[2:3], v[2:3], v[58:59], v[104:105]
	v_add_f32_dpp v110, v110, v110 quad_perm:[2,3,0,1] row_mask:0xf bank_mask:0xf bound_ctrl:1
	v_pk_fma_f32 v[4:5], v[4:5], v[60:61], v[106:107]
	v_pk_fma_f32 v[6:7], v[6:7], v[62:63], v[108:109]
	v_add_f32_dpp v112, v110, v110 row_half_mirror row_mask:0xf bank_mask:0xf bound_ctrl:1
	v_pk_fma_f32 v[0:1], v[64:65], v[112:113], v[0:1] op_sel_hi:[1,0,1]
	v_pk_fma_f32 v[2:3], v[66:67], v[112:113], v[2:3] op_sel_hi:[1,0,1]
	v_pk_fma_f32 v[4:5], v[68:69], v[112:113], v[4:5] op_sel_hi:[1,0,1]
	v_pk_fma_f32 v[6:7], v[70:71], v[112:113], v[6:7] op_sel_hi:[1,0,1]
	v_pk_mul_f32 v[98:99], v[0:1], v[80:81]
	v_pk_mul_f32 v[100:101], v[2:3], v[82:83]
	v_pk_fma_f32 v[98:99], v[4:5], v[84:85], v[98:99]
	v_pk_fma_f32 v[100:101], v[6:7], v[86:87], v[100:101]
	v_pk_add_f32 v[98:99], v[98:99], v[100:101]
	v_add_f32_e32 v121, v98, v99
	s_waitcnt lgkmcnt(0)
; DEV void scan_tile(const Params& p, int l, int tile, char* smem) {
;     ...
;       auto ldops = [&](ScanOps& o, int sl) {
;         const f32x4* b4 = (const f32x4*)(cb + sl * 384);
;         o.nkk0 = b4[cg * 2]; o.nkk1 = b4[cg * 2 + 1];
;         o.w0 = b4[16 + cg * 2]; o.w1 = b4[16 + cg * 2 + 1];
;         o.kka0 = b4[32 + cg * 2]; o.kka1 = b4[32 + cg * 2 + 1];
;         o.kd0 = b4[48 + cg * 2]; o.kd1 = b4[48 + cg * 2 + 1];
;         o.r0 = b4[64 + cg * 2]; o.r1 = b4[64 + cg * 2 + 1];
;         o.v = cb[sl * 384 + vo];
;       };
;       float ykeep = 0.f;
;       auto step = [&](const ScanOps& o, int sl) {
;         const f32x4 sA = S0 * o.nkk0 + S1 * o.nkk1;
;         const float sa = red8((sA[0] + sA[1]) + (sA[2] + sA[3]));
;         S0 = S0 * o.w0 + (o.kka0 * sa + o.kd0 * o.v);
;         S1 = S1 * o.w1 + (o.kka1 * sa + o.kd1 * o.v);
;         const f32x4 yA = S0 * o.r0 + S1 * o.r1;
;         const float y = red8((yA[0] + yA[1]) + (yA[2] + yA[3]));
;         ykeep = (cg == (sl & 7)) ? y : ykeep;
;       };
	ds_read_b128 v[48:51], v117 offset:4608
	ds_read_b128 v[52:55], v117 offset:4624
	ds_read_b128 v[56:59], v117 offset:4864
	ds_read_b128 v[60:63], v117 offset:4880
	ds_read_b128 v[64:67], v117 offset:5120
	ds_read_b128 v[68:71], v117 offset:5136
	ds_read_b128 v[72:75], v117 offset:5376
	ds_read_b128 v[76:79], v117 offset:5392
	ds_read_b128 v[80:83], v117 offset:5632
	ds_read_b128 v[84:87], v117 offset:5648
	v_pk_mul_f32 v[92:93], v[0:1], v[8:9]
	v_pk_mul_f32 v[94:95], v[2:3], v[10:11]
	v_pk_fma_f32 v[92:93], v[4:5], v[12:13], v[92:93]
	v_pk_fma_f32 v[94:95], v[6:7], v[14:15], v[94:95]
	v_pk_mul_f32 v[102:103], v[32:33], v[90:91] op_sel_hi:[1,0]
	v_pk_add_f32 v[92:93], v[92:93], v[94:95]
	v_pk_mul_f32 v[104:105], v[34:35], v[90:91] op_sel_hi:[1,0]
	v_add_f32_e32 v110, v92, v93
	v_pk_mul_f32 v[106:107], v[36:37], v[90:91] op_sel_hi:[1,0]
	v_pk_mul_f32 v[108:109], v[38:39], v[90:91] op_sel_hi:[1,0]
	v_add_f32_dpp v110, v110, v110 quad_perm:[1,0,3,2] row_mask:0xf bank_mask:0xf bound_ctrl:1
	v_pk_fma_f32 v[0:1], v[0:1], v[16:17], v[102:103]
	v_pk_fma_f32 v[2:3], v[2:3], v[18:19], v[104:105]
	v_add_f32_dpp v110, v110, v110 quad_perm:[2,3,0,1] row_mask:0xf bank_mask:0xf bound_ctrl:1
	v_pk_fma_f32 v[4:5], v[4:5], v[20:21], v[106:107]
	v_pk_fma_f32 v[6:7], v[6:7], v[22:23], v[108:109]
	v_add_f32_dpp v112, v110, v110 row_half_mirror row_mask:0xf bank_mask:0xf bound_ctrl:1
	v_pk_fma_f32 v[0:1], v[24:25], v[112:113], v[0:1] op_sel_hi:[1,0,1]
	v_pk_fma_f32 v[2:3], v[26:27], v[112:113], v[2:3] op_sel_hi:[1,0,1]
	v_pk_fma_f32 v[4:5], v[28:29], v[112:113], v[4:5] op_sel_hi:[1,0,1]
	v_pk_fma_f32 v[6:7], v[30:31], v[112:113], v[6:7] op_sel_hi:[1,0,1]
	v_pk_mul_f32 v[98:99], v[0:1], v[40:41]
	v_pk_mul_f32 v[100:101], v[2:3], v[42:43]
	v_pk_fma_f32 v[98:99], v[4:5], v[44:45], v[98:99]
	v_pk_fma_f32 v[100:101], v[6:7], v[46:47], v[100:101]
	v_pk_add_f32 v[98:99], v[98:99], v[100:101]
	v_add_f32_e32 v122, v98, v99
	s_waitcnt lgkmcnt(0)
	ds_read_b128 v[8:11], v117 offset:6144
	ds_read_b128 v[12:15], v117 offset:6160
	ds_read_b128 v[16:19], v117 offset:6400
	ds_read_b128 v[20:23], v117 offset:6416
	ds_read_b128 v[24:27], v117 offset:6656
	ds_read_b128 v[28:31], v117 offset:6672
	ds_read_b128 v[32:35], v117 offset:6912
	ds_read_b128 v[36:39], v117 offset:6928
	ds_read_b128 v[40:43], v117 offset:7168
	ds_read_b128 v[44:47], v117 offset:7184
	ds_read2st64_b32 v[88:89], v118 offset0:29 offset1:35
	v_pk_mul_f32 v[92:93], v[0:1], v[48:49]
	v_pk_mul_f32 v[94:95], v[2:3], v[50:51]
	v_pk_fma_f32 v[92:93], v[4:5], v[52:53], v[92:93]
	v_pk_fma_f32 v[94:95], v[6:7], v[54:55], v[94:95]
	v_pk_mul_f32 v[102:103], v[72:73], v[90:91] op_sel:[0,1] op_sel_hi:[1,1]
	v_pk_add_f32 v[92:93], v[92:93], v[94:95]
	v_pk_mul_f32 v[104:105], v[74:75], v[90:91] op_sel:[0,1] op_sel_hi:[1,1]
	v_add_f32_e32 v110, v92, v93
	v_pk_mul_f32 v[106:107], v[76:77], v[90:91] op_sel:[0,1] op_sel_hi:[1,1]
	v_pk_mul_f32 v[108:109], v[78:79], v[90:91] op_sel:[0,1] op_sel_hi:[1,1]
	v_add_f32_dpp v110, v110, v110 quad_perm:[1,0,3,2] row_mask:0xf bank_mask:0xf bound_ctrl:1
	v_pk_fma_f32 v[0:1], v[0:1], v[56:57], v[102:103]
	v_pk_fma_f32 v[2:3], v[2:3], v[58:59], v[104:105]
	v_add_f32_dpp v110, v110, v110 quad_perm:[2,3,0,1] row_mask:0xf bank_mask:0xf bound_ctrl:1
	v_pk_fma_f32 v[4:5], v[4:5], v[60:61], v[106:107]
	v_pk_fma_f32 v[6:7], v[6:7], v[62:63], v[108:109]
	v_add_f32_dpp v112, v110, v110 row_half_mirror row_mask:0xf bank_mask:0xf bound_ctrl:1
	v_pk_fma_f32 v[0:1], v[64:65], v[112:113], v[0:1] op_sel_hi:[1,0,1]
	v_pk_fma_f32 v[2:3], v[66:67], v[112:113], v[2:3] op_sel_hi:[1,0,1]
	v_pk_fma_f32 v[4:5], v[68:69], v[112:113], v[4:5] op_sel_hi:[1,0,1]
	v_pk_fma_f32 v[6:7], v[70:71], v[112:113], v[6:7] op_sel_hi:[1,0,1]
	v_pk_mul_f32 v[98:99], v[0:1], v[80:81]
	v_pk_mul_f32 v[100:101], v[2:3], v[82:83]
	v_pk_fma_f32 v[98:99], v[4:5], v[84:85], v[98:99]
	v_pk_fma_f32 v[100:101], v[6:7], v[86:87], v[100:101]
	v_pk_add_f32 v[98:99], v[98:99], v[100:101]
	v_add_f32_e32 v123, v98, v99
	s_waitcnt lgkmcnt(0)
	ds_read_b128 v[48:51], v117 offset:7680
	ds_read_b128 v[52:55], v117 offset:7696
	ds_read_b128 v[56:59], v117 offset:7936
	ds_read_b128 v[60:63], v117 offset:7952
	ds_read_b128 v[64:67], v117 offset:8192
	ds_read_b128 v[68:71], v117 offset:8208
	ds_read_b128 v[72:75], v117 offset:8448
	ds_read_b128 v[76:79], v117 offset:8464
	ds_read_b128 v[80:83], v117 offset:8704
	ds_read_b128 v[84:87], v117 offset:8720
	v_pk_mul_f32 v[92:93], v[0:1], v[8:9]
	v_pk_mul_f32 v[94:95], v[2:3], v[10:11]
	v_pk_fma_f32 v[92:93], v[4:5], v[12:13], v[92:93]
	v_pk_fma_f32 v[94:95], v[6:7], v[14:15], v[94:95]
	v_pk_mul_f32 v[102:103], v[32:33], v[88:89] op_sel_hi:[1,0]
	v_pk_add_f32 v[92:93], v[92:93], v[94:95]
	v_pk_mul_f32 v[104:105], v[34:35], v[88:89] op_sel_hi:[1,0]
	v_add_f32_e32 v110, v92, v93
	v_pk_mul_f32 v[106:107], v[36:37], v[88:89] op_sel_hi:[1,0]
	v_pk_mul_f32 v[108:109], v[38:39], v[88:89] op_sel_hi:[1,0]
	v_add_f32_dpp v110, v110, v110 quad_perm:[1,0,3,2] row_mask:0xf bank_mask:0xf bound_ctrl:1
	v_pk_fma_f32 v[0:1], v[0:1], v[16:17], v[102:103]
	v_pk_fma_f32 v[2:3], v[2:3], v[18:19], v[104:105]
	v_add_f32_dpp v110, v110, v110 quad_perm:[2,3,0,1] row_mask:0xf bank_mask:0xf bound_ctrl:1
	v_pk_fma_f32 v[4:5], v[4:5], v[20:21], v[106:107]
	v_pk_fma_f32 v[6:7], v[6:7], v[22:23], v[108:109]
	v_add_f32_dpp v112, v110, v110 row_half_mirror row_mask:0xf bank_mask:0xf bound_ctrl:1
	v_pk_fma_f32 v[0:1], v[24:25], v[112:113], v[0:1] op_sel_hi:[1,0,1]
	v_pk_fma_f32 v[2:3], v[26:27], v[112:113], v[2:3] op_sel_hi:[1,0,1]
	v_pk_fma_f32 v[4:5], v[28:29], v[112:113], v[4:5] op_sel_hi:[1,0,1]
	v_pk_fma_f32 v[6:7], v[30:31], v[112:113], v[6:7] op_sel_hi:[1,0,1]
	v_pk_mul_f32 v[98:99], v[0:1], v[40:41]
	v_pk_mul_f32 v[100:101], v[2:3], v[42:43]
	v_pk_fma_f32 v[98:99], v[4:5], v[44:45], v[98:99]
	v_pk_fma_f32 v[100:101], v[6:7], v[46:47], v[100:101]
	v_pk_add_f32 v[98:99], v[98:99], v[100:101]
	v_add_f32_e32 v124, v98, v99
	s_waitcnt lgkmcnt(0)
; DEV void scan_tile(const Params& p, int l, int tile, char* smem) {
;     ...
;       auto ldops = [&](ScanOps& o, int sl) {
;         const f32x4* b4 = (const f32x4*)(cb + sl * 384);
;         o.nkk0 = b4[cg * 2]; o.nkk1 = b4[cg * 2 + 1];
;         o.w0 = b4[16 + cg * 2]; o.w1 = b4[16 + cg * 2 + 1];
;         o.kka0 = b4[32 + cg * 2]; o.kka1 = b4[32 + cg * 2 + 1];
;         o.kd0 = b4[48 + cg * 2]; o.kd1 = b4[48 + cg * 2 + 1];
;         o.r0 = b4[64 + cg * 2]; o.r1 = b4[64 + cg * 2 + 1];
;         o.v = cb[sl * 384 + vo];
;       };
;       float ykeep = 0.f;
;       auto step = [&](const ScanOps& o, int sl) {
;         const f32x4 sA = S0 * o.nkk0 + S1 * o.nkk1;
;         const float sa = red8((sA[0] + sA[1]) + (sA[2] + sA[3]));
;         S0 = S0 * o.w0 + (o.kka0 * sa + o.kd0 * o.v);
;         S1 = S1 * o.w1 + (o.kka1 * sa + o.kd1 * o.v);
;         const f32x4 yA = S0 * o.r0 + S1 * o.r1;
;         const float y = red8((yA[0] + yA[1]) + (yA[2] + yA[3]));
;         ykeep = (cg == (sl & 7)) ? y : ykeep;
;       };
	ds_read_b128 v[8:11], v117 offset:9216
	ds_read_b128 v[12:15], v117 offset:9232
	ds_read_b128 v[16:19], v117 offset:9472
	ds_read_b128 v[20:23], v117 offset:9488
	ds_read_b128 v[24:27], v117 offset:9728
	ds_read_b128 v[28:31], v117 offset:9744
	ds_read_b128 v[32:35], v117 offset:9984
	ds_read_b128 v[36:39], v117 offset:10000
	ds_read_b128 v[40:43], v117 offset:10240
	ds_read_b128 v[44:47], v117 offset:10256
	ds_read2st64_b32 v[90:91], v118 offset0:41 offset1:47
	v_pk_mul_f32 v[92:93], v[0:1], v[48:49]
	v_pk_mul_f32 v[94:95], v[2:3], v[50:51]
	v_pk_fma_f32 v[92:93], v[4:5], v[52:53], v[92:93]
	v_pk_fma_f32 v[94:95], v[6:7], v[54:55], v[94:95]
	v_pk_mul_f32 v[102:103], v[72:73], v[88:89] op_sel:[0,1] op_sel_hi:[1,1]
	v_pk_add_f32 v[92:93], v[92:93], v[94:95]
	v_pk_mul_f32 v[104:105], v[74:75], v[88:89] op_sel:[0,1] op_sel_hi:[1,1]
	v_add_f32_e32 v110, v92, v93
	v_pk_mul_f32 v[106:107], v[76:77], v[88:89] op_sel:[0,1] op_sel_hi:[1,1]
	v_pk_mul_f32 v[108:109], v[78:79], v[88:89] op_sel:[0,1] op_sel_hi:[1,1]
	v_add_f32_dpp v110, v110, v110 quad_perm:[1,0,3,2] row_mask:0xf bank_mask:0xf bound_ctrl:1
	v_pk_fma_f32 v[0:1], v[0:1], v[56:57], v[102:103]
	v_pk_fma_f32 v[2:3], v[2:3], v[58:59], v[104:105]
	v_add_f32_dpp v110, v110, v110 quad_perm:[2,3,0,1] row_mask:0xf bank_mask:0xf bound_ctrl:1
	v_pk_fma_f32 v[4:5], v[4:5], v[60:61], v[106:107]
	v_pk_fma_f32 v[6:7], v[6:7], v[62:63], v[108:109]
	v_add_f32_dpp v112, v110, v110 row_half_mirror row_mask:0xf bank_mask:0xf bound_ctrl:1
	v_pk_fma_f32 v[0:1], v[64:65], v[112:113], v[0:1] op_sel_hi:[1,0,1]
	v_pk_fma_f32 v[2:3], v[66:67], v[112:113], v[2:3] op_sel_hi:[1,0,1]
	v_pk_fma_f32 v[4:5], v[68:69], v[112:113], v[4:5] op_sel_hi:[1,0,1]
	v_pk_fma_f32 v[6:7], v[70:71], v[112:113], v[6:7] op_sel_hi:[1,0,1]
	v_pk_mul_f32 v[98:99], v[0:1], v[80:81]
	v_pk_mul_f32 v[100:101], v[2:3], v[82:83]
	v_pk_fma_f32 v[98:99], v[4:5], v[84:85], v[98:99]
	v_pk_fma_f32 v[100:101], v[6:7], v[86:87], v[100:101]
	v_pk_add_f32 v[98:99], v[98:99], v[100:101]
	v_add_f32_e32 v125, v98, v99
	s_waitcnt lgkmcnt(0)
	ds_read_b128 v[48:51], v117 offset:10752
	ds_read_b128 v[52:55], v117 offset:10768
	ds_read_b128 v[56:59], v117 offset:11008
	ds_read_b128 v[60:63], v117 offset:11024
	ds_read_b128 v[64:67], v117 offset:11264
	ds_read_b128 v[68:71], v117 offset:11280
	ds_read_b128 v[72:75], v117 offset:11520
	ds_read_b128 v[76:79], v117 offset:11536
	ds_read_b128 v[80:83], v117 offset:11776
	ds_read_b128 v[84:87], v117 offset:11792
	v_pk_mul_f32 v[92:93], v[0:1], v[8:9]
	v_pk_mul_f32 v[94:95], v[2:3], v[10:11]
	v_pk_fma_f32 v[92:93], v[4:5], v[12:13], v[92:93]
	v_pk_fma_f32 v[94:95], v[6:7], v[14:15], v[94:95]
	v_pk_mul_f32 v[102:103], v[32:33], v[90:91] op_sel_hi:[1,0]
	v_pk_add_f32 v[92:93], v[92:93], v[94:95]
	v_pk_mul_f32 v[104:105], v[34:35], v[90:91] op_sel_hi:[1,0]
	v_add_f32_e32 v110, v92, v93
	v_pk_mul_f32 v[106:107], v[36:37], v[90:91] op_sel_hi:[1,0]
	v_pk_mul_f32 v[108:109], v[38:39], v[90:91] op_sel_hi:[1,0]
	v_add_f32_dpp v110, v110, v110 quad_perm:[1,0,3,2] row_mask:0xf bank_mask:0xf bound_ctrl:1
	v_pk_fma_f32 v[0:1], v[0:1], v[16:17], v[102:103]
	v_pk_fma_f32 v[2:3], v[2:3], v[18:19], v[104:105]
	v_add_f32_dpp v110, v110, v110 quad_perm:[2,3,0,1] row_mask:0xf bank_mask:0xf bound_ctrl:1
	v_pk_fma_f32 v[4:5], v[4:5], v[20:21], v[106:107]
	v_pk_fma_f32 v[6:7], v[6:7], v[22:23], v[108:109]
	v_add_f32_dpp v112, v110, v110 row_half_mirror row_mask:0xf bank_mask:0xf bound_ctrl:1
	v_pk_fma_f32 v[0:1], v[24:25], v[112:113], v[0:1] op_sel_hi:[1,0,1]
	v_pk_fma_f32 v[2:3], v[26:27], v[112:113], v[2:3] op_sel_hi:[1,0,1]
	v_pk_fma_f32 v[4:5], v[28:29], v[112:113], v[4:5] op_sel_hi:[1,0,1]
	v_pk_fma_f32 v[6:7], v[30:31], v[112:113], v[6:7] op_sel_hi:[1,0,1]
	v_pk_mul_f32 v[98:99], v[0:1], v[40:41]
	v_pk_mul_f32 v[100:101], v[2:3], v[42:43]
	v_pk_fma_f32 v[98:99], v[4:5], v[44:45], v[98:99]
	v_pk_fma_f32 v[100:101], v[6:7], v[46:47], v[100:101]
	v_pk_add_f32 v[98:99], v[98:99], v[100:101]
	v_add_f32_e32 v126, v98, v99
	s_waitcnt lgkmcnt(0)
	ds_read_b128 v[8:11], v117 offset:12288
	ds_read_b128 v[12:15], v117 offset:12304
	ds_read_b128 v[16:19], v117 offset:12544
	ds_read_b128 v[20:23], v117 offset:12560
	ds_read_b128 v[24:27], v117 offset:12800
	ds_read_b128 v[28:31], v117 offset:12816
	ds_read_b128 v[32:35], v117 offset:13056
	ds_read_b128 v[36:39], v117 offset:13072
	ds_read_b128 v[40:43], v117 offset:13312
	ds_read_b128 v[44:47], v117 offset:13328
	ds_read2st64_b32 v[88:89], v118 offset0:53 offset1:59
	v_pk_mul_f32 v[92:93], v[0:1], v[48:49]
	v_pk_mul_f32 v[94:95], v[2:3], v[50:51]
	v_pk_fma_f32 v[92:93], v[4:5], v[52:53], v[92:93]
	v_pk_fma_f32 v[94:95], v[6:7], v[54:55], v[94:95]
	v_pk_mul_f32 v[102:103], v[72:73], v[90:91] op_sel:[0,1] op_sel_hi:[1,1]
	v_pk_add_f32 v[92:93], v[92:93], v[94:95]
	v_pk_mul_f32 v[104:105], v[74:75], v[90:91] op_sel:[0,1] op_sel_hi:[1,1]
	v_add_f32_e32 v110, v92, v93
	v_pk_mul_f32 v[106:107], v[76:77], v[90:91] op_sel:[0,1] op_sel_hi:[1,1]
	v_pk_mul_f32 v[108:109], v[78:79], v[90:91] op_sel:[0,1] op_sel_hi:[1,1]
	v_add_f32_dpp v110, v110, v110 quad_perm:[1,0,3,2] row_mask:0xf bank_mask:0xf bound_ctrl:1
	v_pk_fma_f32 v[0:1], v[0:1], v[56:57], v[102:103]
	v_pk_fma_f32 v[2:3], v[2:3], v[58:59], v[104:105]
	v_add_f32_dpp v110, v110, v110 quad_perm:[2,3,0,1] row_mask:0xf bank_mask:0xf bound_ctrl:1
	v_pk_fma_f32 v[4:5], v[4:5], v[60:61], v[106:107]
	v_pk_fma_f32 v[6:7], v[6:7], v[62:63], v[108:109]
	v_add_f32_dpp v112, v110, v110 row_half_mirror row_mask:0xf bank_mask:0xf bound_ctrl:1
	v_pk_fma_f32 v[0:1], v[64:65], v[112:113], v[0:1] op_sel_hi:[1,0,1]
	v_pk_fma_f32 v[2:3], v[66:67], v[112:113], v[2:3] op_sel_hi:[1,0,1]
; DEV void scan_tile(const Params& p, int l, int tile, char* smem) {
;     ...
;       auto ldops = [&](ScanOps& o, int sl) {
;         const f32x4* b4 = (const f32x4*)(cb + sl * 384);
;         o.nkk0 = b4[cg * 2]; o.nkk1 = b4[cg * 2 + 1];
;         o.w0 = b4[16 + cg * 2]; o.w1 = b4[16 + cg * 2 + 1];
;         o.kka0 = b4[32 + cg * 2]; o.kka1 = b4[32 + cg * 2 + 1];
;         o.kd0 = b4[48 + cg * 2]; o.kd1 = b4[48 + cg * 2 + 1];
;         o.r0 = b4[64 + cg * 2]; o.r1 = b4[64 + cg * 2 + 1];
;         o.v = cb[sl * 384 + vo];
;       };
;       float ykeep = 0.f;
;       auto step = [&](const ScanOps& o, int sl) {
;         const f32x4 sA = S0 * o.nkk0 + S1 * o.nkk1;
;         const float sa = red8((sA[0] + sA[1]) + (sA[2] + sA[3]));
;         S0 = S0 * o.w0 + (o.kka0 * sa + o.kd0 * o.v);
;         S1 = S1 * o.w1 + (o.kka1 * sa + o.kd1 * o.v);
;         const f32x4 yA = S0 * o.r0 + S1 * o.r1;
;         const float y = red8((yA[0] + yA[1]) + (yA[2] + yA[3]));
;         ykeep = (cg == (sl & 7)) ? y : ykeep;
;       };
;       ScanOps oa, ob;
;       ldops(oa, 0);
; #pragma unroll
;       for (int s8 = 0; s8 < 32; s8 += 8) {
; #pragma unroll
;         for (int q = 0; q < 8; q += 2) {
;           ldops(ob, s8 + q + 1);
;           step(oa, s8 + q);
;           ldops(oa, (s8 + q + 2) & 31);
;           step(ob, s8 + q + 1);
;         }
;         yw[s8 * 32] = ykeep;
;       }
	v_pk_fma_f32 v[4:5], v[68:69], v[112:113], v[4:5] op_sel_hi:[1,0,1]
	v_pk_fma_f32 v[6:7], v[70:71], v[112:113], v[6:7] op_sel_hi:[1,0,1]
	v_pk_mul_f32 v[98:99], v[0:1], v[80:81]
	v_pk_mul_f32 v[100:101], v[2:3], v[82:83]
	v_pk_fma_f32 v[98:99], v[4:5], v[84:85], v[98:99]
	v_pk_fma_f32 v[100:101], v[6:7], v[86:87], v[100:101]
	v_pk_add_f32 v[98:99], v[98:99], v[100:101]
	v_add_f32_e32 v127, v98, v99
	v_add_f32_dpp v120, v120, v120 row_half_mirror row_mask:0xf bank_mask:0x5 bound_ctrl:1
	v_add_f32_dpp v120, v124, v124 row_half_mirror row_mask:0xf bank_mask:0xa bound_ctrl:1
	v_add_f32_dpp v121, v121, v121 row_half_mirror row_mask:0xf bank_mask:0x5 bound_ctrl:1
	v_add_f32_dpp v121, v125, v125 row_half_mirror row_mask:0xf bank_mask:0xa bound_ctrl:1
	v_add_f32_dpp v122, v122, v122 row_half_mirror row_mask:0xf bank_mask:0x5 bound_ctrl:1
	v_add_f32_dpp v122, v126, v126 row_half_mirror row_mask:0xf bank_mask:0xa bound_ctrl:1
	v_add_f32_dpp v123, v123, v123 row_half_mirror row_mask:0xf bank_mask:0x5 bound_ctrl:1
	v_add_f32_dpp v123, v127, v127 row_half_mirror row_mask:0xf bank_mask:0xa bound_ctrl:1
	v_add_f32_dpp v120, v120, v120 quad_perm:[2,3,0,1] row_mask:0xf bank_mask:0xf bound_ctrl:1
	v_add_f32_dpp v121, v121, v121 quad_perm:[2,3,0,1] row_mask:0xf bank_mask:0xf bound_ctrl:1
	v_add_f32_dpp v122, v122, v122 quad_perm:[2,3,0,1] row_mask:0xf bank_mask:0xf bound_ctrl:1
	v_add_f32_dpp v123, v123, v123 quad_perm:[2,3,0,1] row_mask:0xf bank_mask:0xf bound_ctrl:1
	v_cndmask_b32_e64 v124, v122, v120, s[62:63]
	v_cndmask_b32_e64 v125, v123, v121, s[62:63]
	s_nop 0
	v_add_f32_dpp v124, v124, v124 quad_perm:[1,0,3,2] row_mask:0xf bank_mask:0xf bound_ctrl:1
	v_add_f32_dpp v125, v125, v125 quad_perm:[1,0,3,2] row_mask:0xf bank_mask:0xf bound_ctrl:1
	v_cndmask_b32_e64 v126, v125, v124, s[64:65]
	ds_write_b32 v119, v126 offset:0
	s_waitcnt lgkmcnt(1)
	ds_read_b128 v[48:51], v117 offset:13824
	ds_read_b128 v[52:55], v117 offset:13840
	ds_read_b128 v[56:59], v117 offset:14080
	ds_read_b128 v[60:63], v117 offset:14096
	ds_read_b128 v[64:67], v117 offset:14336
	ds_read_b128 v[68:71], v117 offset:14352
	ds_read_b128 v[72:75], v117 offset:14592
	ds_read_b128 v[76:79], v117 offset:14608
	ds_read_b128 v[80:83], v117 offset:14848
	ds_read_b128 v[84:87], v117 offset:14864
	v_pk_mul_f32 v[92:93], v[0:1], v[8:9]
	v_pk_mul_f32 v[94:95], v[2:3], v[10:11]
	v_pk_fma_f32 v[92:93], v[4:5], v[12:13], v[92:93]
	v_pk_fma_f32 v[94:95], v[6:7], v[14:15], v[94:95]
	v_pk_mul_f32 v[102:103], v[32:33], v[88:89] op_sel_hi:[1,0]
	v_pk_add_f32 v[92:93], v[92:93], v[94:95]
	v_pk_mul_f32 v[104:105], v[34:35], v[88:89] op_sel_hi:[1,0]
	v_add_f32_e32 v110, v92, v93
	v_pk_mul_f32 v[106:107], v[36:37], v[88:89] op_sel_hi:[1,0]
	v_pk_mul_f32 v[108:109], v[38:39], v[88:89] op_sel_hi:[1,0]
	v_add_f32_dpp v110, v110, v110 quad_perm:[1,0,3,2] row_mask:0xf bank_mask:0xf bound_ctrl:1
	v_pk_fma_f32 v[0:1], v[0:1], v[16:17], v[102:103]
	v_pk_fma_f32 v[2:3], v[2:3], v[18:19], v[104:105]
	v_add_f32_dpp v110, v110, v110 quad_perm:[2,3,0,1] row_mask:0xf bank_mask:0xf bound_ctrl:1
	v_pk_fma_f32 v[4:5], v[4:5], v[20:21], v[106:107]
	v_pk_fma_f32 v[6:7], v[6:7], v[22:23], v[108:109]
	v_add_f32_dpp v112, v110, v110 row_half_mirror row_mask:0xf bank_mask:0xf bound_ctrl:1
	v_pk_fma_f32 v[0:1], v[24:25], v[112:113], v[0:1] op_sel_hi:[1,0,1]
	v_pk_fma_f32 v[2:3], v[26:27], v[112:113], v[2:3] op_sel_hi:[1,0,1]
	v_pk_fma_f32 v[4:5], v[28:29], v[112:113], v[4:5] op_sel_hi:[1,0,1]
	v_pk_fma_f32 v[6:7], v[30:31], v[112:113], v[6:7] op_sel_hi:[1,0,1]
	v_pk_mul_f32 v[98:99], v[0:1], v[40:41]
	v_pk_mul_f32 v[100:101], v[2:3], v[42:43]
	v_pk_fma_f32 v[98:99], v[4:5], v[44:45], v[98:99]
	v_pk_fma_f32 v[100:101], v[6:7], v[46:47], v[100:101]
	v_pk_add_f32 v[98:99], v[98:99], v[100:101]
	v_add_f32_e32 v120, v98, v99
	s_waitcnt lgkmcnt(0)
	ds_read_b128 v[8:11], v117 offset:15360
	ds_read_b128 v[12:15], v117 offset:15376
	ds_read_b128 v[16:19], v117 offset:15616
	ds_read_b128 v[20:23], v117 offset:15632
	ds_read_b128 v[24:27], v117 offset:15872
	ds_read_b128 v[28:31], v117 offset:15888
	ds_read_b128 v[32:35], v117 offset:16128
	ds_read_b128 v[36:39], v117 offset:16144
	ds_read_b128 v[40:43], v117 offset:16384
	ds_read_b128 v[44:47], v117 offset:16400
	ds_read2st64_b32 v[90:91], v118 offset0:65 offset1:71
	v_pk_mul_f32 v[92:93], v[0:1], v[48:49]
	v_pk_mul_f32 v[94:95], v[2:3], v[50:51]
	v_pk_fma_f32 v[92:93], v[4:5], v[52:53], v[92:93]
	v_pk_fma_f32 v[94:95], v[6:7], v[54:55], v[94:95]
	v_pk_mul_f32 v[102:103], v[72:73], v[88:89] op_sel:[0,1] op_sel_hi:[1,1]
	v_pk_add_f32 v[92:93], v[92:93], v[94:95]
	v_pk_mul_f32 v[104:105], v[74:75], v[88:89] op_sel:[0,1] op_sel_hi:[1,1]
	v_add_f32_e32 v110, v92, v93
	v_pk_mul_f32 v[106:107], v[76:77], v[88:89] op_sel:[0,1] op_sel_hi:[1,1]
	v_pk_mul_f32 v[108:109], v[78:79], v[88:89] op_sel:[0,1] op_sel_hi:[1,1]
	v_add_f32_dpp v110, v110, v110 quad_perm:[1,0,3,2] row_mask:0xf bank_mask:0xf bound_ctrl:1
	v_pk_fma_f32 v[0:1], v[0:1], v[56:57], v[102:103]
	v_pk_fma_f32 v[2:3], v[2:3], v[58:59], v[104:105]
	v_add_f32_dpp v110, v110, v110 quad_perm:[2,3,0,1] row_mask:0xf bank_mask:0xf bound_ctrl:1
	v_pk_fma_f32 v[4:5], v[4:5], v[60:61], v[106:107]
	v_pk_fma_f32 v[6:7], v[6:7], v[62:63], v[108:109]
	v_add_f32_dpp v112, v110, v110 row_half_mirror row_mask:0xf bank_mask:0xf bound_ctrl:1
	v_pk_fma_f32 v[0:1], v[64:65], v[112:113], v[0:1] op_sel_hi:[1,0,1]
	v_pk_fma_f32 v[2:3], v[66:67], v[112:113], v[2:3] op_sel_hi:[1,0,1]
	v_pk_fma_f32 v[4:5], v[68:69], v[112:113], v[4:5] op_sel_hi:[1,0,1]
	v_pk_fma_f32 v[6:7], v[70:71], v[112:113], v[6:7] op_sel_hi:[1,0,1]
	v_pk_mul_f32 v[98:99], v[0:1], v[80:81]
	v_pk_mul_f32 v[100:101], v[2:3], v[82:83]
	v_pk_fma_f32 v[98:99], v[4:5], v[84:85], v[98:99]
	v_pk_fma_f32 v[100:101], v[6:7], v[86:87], v[100:101]
	v_pk_add_f32 v[98:99], v[98:99], v[100:101]
	v_add_f32_e32 v121, v98, v99
	s_waitcnt lgkmcnt(0)
; DEV void scan_tile(const Params& p, int l, int tile, char* smem) {
;     ...
;       auto ldops = [&](ScanOps& o, int sl) {
;         const f32x4* b4 = (const f32x4*)(cb + sl * 384);
;         o.nkk0 = b4[cg * 2]; o.nkk1 = b4[cg * 2 + 1];
;         o.w0 = b4[16 + cg * 2]; o.w1 = b4[16 + cg * 2 + 1];
;         o.kka0 = b4[32 + cg * 2]; o.kka1 = b4[32 + cg * 2 + 1];
;         o.kd0 = b4[48 + cg * 2]; o.kd1 = b4[48 + cg * 2 + 1];
;         o.r0 = b4[64 + cg * 2]; o.r1 = b4[64 + cg * 2 + 1];
;         o.v = cb[sl * 384 + vo];
;       };
;       float ykeep = 0.f;
;       auto step = [&](const ScanOps& o, int sl) {
;         const f32x4 sA = S0 * o.nkk0 + S1 * o.nkk1;
;         const float sa = red8((sA[0] + sA[1]) + (sA[2] + sA[3]));
;         S0 = S0 * o.w0 + (o.kka0 * sa + o.kd0 * o.v);
;         S1 = S1 * o.w1 + (o.kka1 * sa + o.kd1 * o.v);
;         const f32x4 yA = S0 * o.r0 + S1 * o.r1;
;         const float y = red8((yA[0] + yA[1]) + (yA[2] + yA[3]));
;         ykeep = (cg == (sl & 7)) ? y : ykeep;
;       };
;       ScanOps oa, ob;
;       ldops(oa, 0);
; #pragma unroll
;       for (int s8 = 0; s8 < 32; s8 += 8) {
; #pragma unroll
;         for (int q = 0; q < 8; q += 2) {
;           ldops(ob, s8 + q + 1);
;           step(oa, s8 + q);
;           ldops(oa, (s8 + q + 2) & 31);
;           step(ob, s8 + q + 1);
;         }
;         yw[s8 * 32] = ykeep;
;       }
	ds_read_b128 v[48:51], v117 offset:16896
	ds_read_b128 v[52:55], v117 offset:16912
	ds_read_b128 v[56:59], v117 offset:17152
	ds_read_b128 v[60:63], v117 offset:17168
	ds_read_b128 v[64:67], v117 offset:17408
	ds_read_b128 v[68:71], v117 offset:17424
	ds_read_b128 v[72:75], v117 offset:17664
	ds_read_b128 v[76:79], v117 offset:17680
	ds_read_b128 v[80:83], v117 offset:17920
	ds_read_b128 v[84:87], v117 offset:17936
	v_pk_mul_f32 v[92:93], v[0:1], v[8:9]
	v_pk_mul_f32 v[94:95], v[2:3], v[10:11]
	v_pk_fma_f32 v[92:93], v[4:5], v[12:13], v[92:93]
	v_pk_fma_f32 v[94:95], v[6:7], v[14:15], v[94:95]
	v_pk_mul_f32 v[102:103], v[32:33], v[90:91] op_sel_hi:[1,0]
	v_pk_add_f32 v[92:93], v[92:93], v[94:95]
	v_pk_mul_f32 v[104:105], v[34:35], v[90:91] op_sel_hi:[1,0]
	v_add_f32_e32 v110, v92, v93
	v_pk_mul_f32 v[106:107], v[36:37], v[90:91] op_sel_hi:[1,0]
	v_pk_mul_f32 v[108:109], v[38:39], v[90:91] op_sel_hi:[1,0]
	v_add_f32_dpp v110, v110, v110 quad_perm:[1,0,3,2] row_mask:0xf bank_mask:0xf bound_ctrl:1
	v_pk_fma_f32 v[0:1], v[0:1], v[16:17], v[102:103]
	v_pk_fma_f32 v[2:3], v[2:3], v[18:19], v[104:105]
	v_add_f32_dpp v110, v110, v110 quad_perm:[2,3,0,1] row_mask:0xf bank_mask:0xf bound_ctrl:1
	v_pk_fma_f32 v[4:5], v[4:5], v[20:21], v[106:107]
	v_pk_fma_f32 v[6:7], v[6:7], v[22:23], v[108:109]
	v_add_f32_dpp v112, v110, v110 row_half_mirror row_mask:0xf bank_mask:0xf bound_ctrl:1
	v_pk_fma_f32 v[0:1], v[24:25], v[112:113], v[0:1] op_sel_hi:[1,0,1]
	v_pk_fma_f32 v[2:3], v[26:27], v[112:113], v[2:3] op_sel_hi:[1,0,1]
	v_pk_fma_f32 v[4:5], v[28:29], v[112:113], v[4:5] op_sel_hi:[1,0,1]
	v_pk_fma_f32 v[6:7], v[30:31], v[112:113], v[6:7] op_sel_hi:[1,0,1]
	v_pk_mul_f32 v[98:99], v[0:1], v[40:41]
	v_pk_mul_f32 v[100:101], v[2:3], v[42:43]
	v_pk_fma_f32 v[98:99], v[4:5], v[44:45], v[98:99]
	v_pk_fma_f32 v[100:101], v[6:7], v[46:47], v[100:101]
	v_pk_add_f32 v[98:99], v[98:99], v[100:101]
	v_add_f32_e32 v122, v98, v99
	s_waitcnt lgkmcnt(0)
	ds_read_b128 v[8:11], v117 offset:18432
	ds_read_b128 v[12:15], v117 offset:18448
	ds_read_b128 v[16:19], v117 offset:18688
	ds_read_b128 v[20:23], v117 offset:18704
	ds_read_b128 v[24:27], v117 offset:18944
	ds_read_b128 v[28:31], v117 offset:18960
	ds_read_b128 v[32:35], v117 offset:19200
	ds_read_b128 v[36:39], v117 offset:19216
	ds_read_b128 v[40:43], v117 offset:19456
	ds_read_b128 v[44:47], v117 offset:19472
	ds_read2st64_b32 v[88:89], v118 offset0:77 offset1:83
	v_pk_mul_f32 v[92:93], v[0:1], v[48:49]
	v_pk_mul_f32 v[94:95], v[2:3], v[50:51]
	v_pk_fma_f32 v[92:93], v[4:5], v[52:53], v[92:93]
	v_pk_fma_f32 v[94:95], v[6:7], v[54:55], v[94:95]
	v_pk_mul_f32 v[102:103], v[72:73], v[90:91] op_sel:[0,1] op_sel_hi:[1,1]
	v_pk_add_f32 v[92:93], v[92:93], v[94:95]
	v_pk_mul_f32 v[104:105], v[74:75], v[90:91] op_sel:[0,1] op_sel_hi:[1,1]
	v_add_f32_e32 v110, v92, v93
	v_pk_mul_f32 v[106:107], v[76:77], v[90:91] op_sel:[0,1] op_sel_hi:[1,1]
	v_pk_mul_f32 v[108:109], v[78:79], v[90:91] op_sel:[0,1] op_sel_hi:[1,1]
	v_add_f32_dpp v110, v110, v110 quad_perm:[1,0,3,2] row_mask:0xf bank_mask:0xf bound_ctrl:1
	v_pk_fma_f32 v[0:1], v[0:1], v[56:57], v[102:103]
	v_pk_fma_f32 v[2:3], v[2:3], v[58:59], v[104:105]
	v_add_f32_dpp v110, v110, v110 quad_perm:[2,3,0,1] row_mask:0xf bank_mask:0xf bound_ctrl:1
	v_pk_fma_f32 v[4:5], v[4:5], v[60:61], v[106:107]
	v_pk_fma_f32 v[6:7], v[6:7], v[62:63], v[108:109]
	v_add_f32_dpp v112, v110, v110 row_half_mirror row_mask:0xf bank_mask:0xf bound_ctrl:1
	v_pk_fma_f32 v[0:1], v[64:65], v[112:113], v[0:1] op_sel_hi:[1,0,1]
	v_pk_fma_f32 v[2:3], v[66:67], v[112:113], v[2:3] op_sel_hi:[1,0,1]
	v_pk_fma_f32 v[4:5], v[68:69], v[112:113], v[4:5] op_sel_hi:[1,0,1]
	v_pk_fma_f32 v[6:7], v[70:71], v[112:113], v[6:7] op_sel_hi:[1,0,1]
	v_pk_mul_f32 v[98:99], v[0:1], v[80:81]
	v_pk_mul_f32 v[100:101], v[2:3], v[82:83]
	v_pk_fma_f32 v[98:99], v[4:5], v[84:85], v[98:99]
	v_pk_fma_f32 v[100:101], v[6:7], v[86:87], v[100:101]
	v_pk_add_f32 v[98:99], v[98:99], v[100:101]
	v_add_f32_e32 v123, v98, v99
	s_waitcnt lgkmcnt(0)
	ds_read_b128 v[48:51], v117 offset:19968
	ds_read_b128 v[52:55], v117 offset:19984
	ds_read_b128 v[56:59], v117 offset:20224
	ds_read_b128 v[60:63], v117 offset:20240
	ds_read_b128 v[64:67], v117 offset:20480
	ds_read_b128 v[68:71], v117 offset:20496
	ds_read_b128 v[72:75], v117 offset:20736
	ds_read_b128 v[76:79], v117 offset:20752
	ds_read_b128 v[80:83], v117 offset:20992
	ds_read_b128 v[84:87], v117 offset:21008
	v_pk_mul_f32 v[92:93], v[0:1], v[8:9]
	v_pk_mul_f32 v[94:95], v[2:3], v[10:11]
	v_pk_fma_f32 v[92:93], v[4:5], v[12:13], v[92:93]
	v_pk_fma_f32 v[94:95], v[6:7], v[14:15], v[94:95]
	v_pk_mul_f32 v[102:103], v[32:33], v[88:89] op_sel_hi:[1,0]
	v_pk_add_f32 v[92:93], v[92:93], v[94:95]
	v_pk_mul_f32 v[104:105], v[34:35], v[88:89] op_sel_hi:[1,0]
	v_add_f32_e32 v110, v92, v93
	v_pk_mul_f32 v[106:107], v[36:37], v[88:89] op_sel_hi:[1,0]
	v_pk_mul_f32 v[108:109], v[38:39], v[88:89] op_sel_hi:[1,0]
	v_add_f32_dpp v110, v110, v110 quad_perm:[1,0,3,2] row_mask:0xf bank_mask:0xf bound_ctrl:1
	v_pk_fma_f32 v[0:1], v[0:1], v[16:17], v[102:103]
	v_pk_fma_f32 v[2:3], v[2:3], v[18:19], v[104:105]
	v_add_f32_dpp v110, v110, v110 quad_perm:[2,3,0,1] row_mask:0xf bank_mask:0xf bound_ctrl:1
	v_pk_fma_f32 v[4:5], v[4:5], v[20:21], v[106:107]
	v_pk_fma_f32 v[6:7], v[6:7], v[22:23], v[108:109]
	v_add_f32_dpp v112, v110, v110 row_half_mirror row_mask:0xf bank_mask:0xf bound_ctrl:1
	v_pk_fma_f32 v[0:1], v[24:25], v[112:113], v[0:1] op_sel_hi:[1,0,1]
	v_pk_fma_f32 v[2:3], v[26:27], v[112:113], v[2:3] op_sel_hi:[1,0,1]
	v_pk_fma_f32 v[4:5], v[28:29], v[112:113], v[4:5] op_sel_hi:[1,0,1]
	v_pk_fma_f32 v[6:7], v[30:31], v[112:113], v[6:7] op_sel_hi:[1,0,1]
	v_pk_mul_f32 v[98:99], v[0:1], v[40:41]
	v_pk_mul_f32 v[100:101], v[2:3], v[42:43]
	v_pk_fma_f32 v[98:99], v[4:5], v[44:45], v[98:99]
	v_pk_fma_f32 v[100:101], v[6:7], v[46:47], v[100:101]
	v_pk_add_f32 v[98:99], v[98:99], v[100:101]
	v_add_f32_e32 v124, v98, v99
	s_waitcnt lgkmcnt(0)
; DEV void scan_tile(const Params& p, int l, int tile, char* smem) {
;     ...
;       auto ldops = [&](ScanOps& o, int sl) {
;         const f32x4* b4 = (const f32x4*)(cb + sl * 384);
;         o.nkk0 = b4[cg * 2]; o.nkk1 = b4[cg * 2 + 1];
;         o.w0 = b4[16 + cg * 2]; o.w1 = b4[16 + cg * 2 + 1];
;         o.kka0 = b4[32 + cg * 2]; o.kka1 = b4[32 + cg * 2 + 1];
;         o.kd0 = b4[48 + cg * 2]; o.kd1 = b4[48 + cg * 2 + 1];
;         o.r0 = b4[64 + cg * 2]; o.r1 = b4[64 + cg * 2 + 1];
;         o.v = cb[sl * 384 + vo];
;       };
;       float ykeep = 0.f;
;       auto step = [&](const ScanOps& o, int sl) {
;         const f32x4 sA = S0 * o.nkk0 + S1 * o.nkk1;
;         const float sa = red8((sA[0] + sA[1]) + (sA[2] + sA[3]));
;         S0 = S0 * o.w0 + (o.kka0 * sa + o.kd0 * o.v);
;         S1 = S1 * o.w1 + (o.kka1 * sa + o.kd1 * o.v);
;         const f32x4 yA = S0 * o.r0 + S1 * o.r1;
;         const float y = red8((yA[0] + yA[1]) + (yA[2] + yA[3]));
;         ykeep = (cg == (sl & 7)) ? y : ykeep;
;       };
;       ScanOps oa, ob;
;       ldops(oa, 0);
; #pragma unroll
;       for (int s8 = 0; s8 < 32; s8 += 8) {
; #pragma unroll
;         for (int q = 0; q < 8; q += 2) {
;           ldops(ob, s8 + q + 1);
;           step(oa, s8 + q);
;           ldops(oa, (s8 + q + 2) & 31);
;           step(ob, s8 + q + 1);
;         }
;         yw[s8 * 32] = ykeep;
;       }
	ds_read_b128 v[8:11], v117 offset:21504
	ds_read_b128 v[12:15], v117 offset:21520
	ds_read_b128 v[16:19], v117 offset:21760
	ds_read_b128 v[20:23], v117 offset:21776
	ds_read_b128 v[24:27], v117 offset:22016
	ds_read_b128 v[28:31], v117 offset:22032
	ds_read_b128 v[32:35], v117 offset:22272
	ds_read_b128 v[36:39], v117 offset:22288
	ds_read_b128 v[40:43], v117 offset:22528
	ds_read_b128 v[44:47], v117 offset:22544
	ds_read2st64_b32 v[90:91], v118 offset0:89 offset1:95
	v_pk_mul_f32 v[92:93], v[0:1], v[48:49]
	v_pk_mul_f32 v[94:95], v[2:3], v[50:51]
	v_pk_fma_f32 v[92:93], v[4:5], v[52:53], v[92:93]
	v_pk_fma_f32 v[94:95], v[6:7], v[54:55], v[94:95]
	v_pk_mul_f32 v[102:103], v[72:73], v[88:89] op_sel:[0,1] op_sel_hi:[1,1]
	v_pk_add_f32 v[92:93], v[92:93], v[94:95]
	v_pk_mul_f32 v[104:105], v[74:75], v[88:89] op_sel:[0,1] op_sel_hi:[1,1]
	v_add_f32_e32 v110, v92, v93
	v_pk_mul_f32 v[106:107], v[76:77], v[88:89] op_sel:[0,1] op_sel_hi:[1,1]
	v_pk_mul_f32 v[108:109], v[78:79], v[88:89] op_sel:[0,1] op_sel_hi:[1,1]
	v_add_f32_dpp v110, v110, v110 quad_perm:[1,0,3,2] row_mask:0xf bank_mask:0xf bound_ctrl:1
	v_pk_fma_f32 v[0:1], v[0:1], v[56:57], v[102:103]
	v_pk_fma_f32 v[2:3], v[2:3], v[58:59], v[104:105]
	v_add_f32_dpp v110, v110, v110 quad_perm:[2,3,0,1] row_mask:0xf bank_mask:0xf bound_ctrl:1
	v_pk_fma_f32 v[4:5], v[4:5], v[60:61], v[106:107]
	v_pk_fma_f32 v[6:7], v[6:7], v[62:63], v[108:109]
	v_add_f32_dpp v112, v110, v110 row_half_mirror row_mask:0xf bank_mask:0xf bound_ctrl:1
	v_pk_fma_f32 v[0:1], v[64:65], v[112:113], v[0:1] op_sel_hi:[1,0,1]
	v_pk_fma_f32 v[2:3], v[66:67], v[112:113], v[2:3] op_sel_hi:[1,0,1]
	v_pk_fma_f32 v[4:5], v[68:69], v[112:113], v[4:5] op_sel_hi:[1,0,1]
	v_pk_fma_f32 v[6:7], v[70:71], v[112:113], v[6:7] op_sel_hi:[1,0,1]
	v_pk_mul_f32 v[98:99], v[0:1], v[80:81]
	v_pk_mul_f32 v[100:101], v[2:3], v[82:83]
	v_pk_fma_f32 v[98:99], v[4:5], v[84:85], v[98:99]
	v_pk_fma_f32 v[100:101], v[6:7], v[86:87], v[100:101]
	v_pk_add_f32 v[98:99], v[98:99], v[100:101]
	v_add_f32_e32 v125, v98, v99
	s_waitcnt lgkmcnt(0)
	ds_read_b128 v[48:51], v117 offset:23040
	ds_read_b128 v[52:55], v117 offset:23056
	ds_read_b128 v[56:59], v117 offset:23296
	ds_read_b128 v[60:63], v117 offset:23312
	ds_read_b128 v[64:67], v117 offset:23552
	ds_read_b128 v[68:71], v117 offset:23568
	ds_read_b128 v[72:75], v117 offset:23808
	ds_read_b128 v[76:79], v117 offset:23824
	ds_read_b128 v[80:83], v117 offset:24064
	ds_read_b128 v[84:87], v117 offset:24080
	v_pk_mul_f32 v[92:93], v[0:1], v[8:9]
	v_pk_mul_f32 v[94:95], v[2:3], v[10:11]
	v_pk_fma_f32 v[92:93], v[4:5], v[12:13], v[92:93]
	v_pk_fma_f32 v[94:95], v[6:7], v[14:15], v[94:95]
	v_pk_mul_f32 v[102:103], v[32:33], v[90:91] op_sel_hi:[1,0]
	v_pk_add_f32 v[92:93], v[92:93], v[94:95]
	v_pk_mul_f32 v[104:105], v[34:35], v[90:91] op_sel_hi:[1,0]
	v_add_f32_e32 v110, v92, v93
	v_pk_mul_f32 v[106:107], v[36:37], v[90:91] op_sel_hi:[1,0]
	v_pk_mul_f32 v[108:109], v[38:39], v[90:91] op_sel_hi:[1,0]
	v_add_f32_dpp v110, v110, v110 quad_perm:[1,0,3,2] row_mask:0xf bank_mask:0xf bound_ctrl:1
	v_pk_fma_f32 v[0:1], v[0:1], v[16:17], v[102:103]
	v_pk_fma_f32 v[2:3], v[2:3], v[18:19], v[104:105]
	v_add_f32_dpp v110, v110, v110 quad_perm:[2,3,0,1] row_mask:0xf bank_mask:0xf bound_ctrl:1
	v_pk_fma_f32 v[4:5], v[4:5], v[20:21], v[106:107]
	v_pk_fma_f32 v[6:7], v[6:7], v[22:23], v[108:109]
	v_add_f32_dpp v112, v110, v110 row_half_mirror row_mask:0xf bank_mask:0xf bound_ctrl:1
	v_pk_fma_f32 v[0:1], v[24:25], v[112:113], v[0:1] op_sel_hi:[1,0,1]
	v_pk_fma_f32 v[2:3], v[26:27], v[112:113], v[2:3] op_sel_hi:[1,0,1]
	v_pk_fma_f32 v[4:5], v[28:29], v[112:113], v[4:5] op_sel_hi:[1,0,1]
	v_pk_fma_f32 v[6:7], v[30:31], v[112:113], v[6:7] op_sel_hi:[1,0,1]
	v_pk_mul_f32 v[98:99], v[0:1], v[40:41]
	v_pk_mul_f32 v[100:101], v[2:3], v[42:43]
	v_pk_fma_f32 v[98:99], v[4:5], v[44:45], v[98:99]
	v_pk_fma_f32 v[100:101], v[6:7], v[46:47], v[100:101]
	v_pk_add_f32 v[98:99], v[98:99], v[100:101]
	v_add_f32_e32 v126, v98, v99
	s_waitcnt lgkmcnt(0)
	ds_read_b128 v[8:11], v117 offset:24576
	ds_read_b128 v[12:15], v117 offset:24592
	ds_read_b128 v[16:19], v117 offset:24832
	ds_read_b128 v[20:23], v117 offset:24848
	ds_read_b128 v[24:27], v117 offset:25088
	ds_read_b128 v[28:31], v117 offset:25104
	ds_read_b128 v[32:35], v117 offset:25344
	ds_read_b128 v[36:39], v117 offset:25360
	ds_read_b128 v[40:43], v117 offset:25600
	ds_read_b128 v[44:47], v117 offset:25616
	ds_read2st64_b32 v[88:89], v118 offset0:101 offset1:107
	v_pk_mul_f32 v[92:93], v[0:1], v[48:49]
	v_pk_mul_f32 v[94:95], v[2:3], v[50:51]
	v_pk_fma_f32 v[92:93], v[4:5], v[52:53], v[92:93]
	v_pk_fma_f32 v[94:95], v[6:7], v[54:55], v[94:95]
	v_pk_mul_f32 v[102:103], v[72:73], v[90:91] op_sel:[0,1] op_sel_hi:[1,1]
	v_pk_add_f32 v[92:93], v[92:93], v[94:95]
	v_pk_mul_f32 v[104:105], v[74:75], v[90:91] op_sel:[0,1] op_sel_hi:[1,1]
	v_add_f32_e32 v110, v92, v93
	v_pk_mul_f32 v[106:107], v[76:77], v[90:91] op_sel:[0,1] op_sel_hi:[1,1]
	v_pk_mul_f32 v[108:109], v[78:79], v[90:91] op_sel:[0,1] op_sel_hi:[1,1]
	v_add_f32_dpp v110, v110, v110 quad_perm:[1,0,3,2] row_mask:0xf bank_mask:0xf bound_ctrl:1
	v_pk_fma_f32 v[0:1], v[0:1], v[56:57], v[102:103]
	v_pk_fma_f32 v[2:3], v[2:3], v[58:59], v[104:105]
	v_add_f32_dpp v110, v110, v110 quad_perm:[2,3,0,1] row_mask:0xf bank_mask:0xf bound_ctrl:1
	v_pk_fma_f32 v[4:5], v[4:5], v[60:61], v[106:107]
	v_pk_fma_f32 v[6:7], v[6:7], v[62:63], v[108:109]
	v_add_f32_dpp v112, v110, v110 row_half_mirror row_mask:0xf bank_mask:0xf bound_ctrl:1
	v_pk_fma_f32 v[0:1], v[64:65], v[112:113], v[0:1] op_sel_hi:[1,0,1]
	v_pk_fma_f32 v[2:3], v[66:67], v[112:113], v[2:3] op_sel_hi:[1,0,1]
; DEV void scan_tile(const Params& p, int l, int tile, char* smem) {
;     ...
;       auto ldops = [&](ScanOps& o, int sl) {
;         const f32x4* b4 = (const f32x4*)(cb + sl * 384);
;         o.nkk0 = b4[cg * 2]; o.nkk1 = b4[cg * 2 + 1];
;         o.w0 = b4[16 + cg * 2]; o.w1 = b4[16 + cg * 2 + 1];
;         o.kka0 = b4[32 + cg * 2]; o.kka1 = b4[32 + cg * 2 + 1];
;         o.kd0 = b4[48 + cg * 2]; o.kd1 = b4[48 + cg * 2 + 1];
;         o.r0 = b4[64 + cg * 2]; o.r1 = b4[64 + cg * 2 + 1];
;         o.v = cb[sl * 384 + vo];
;       };
;       float ykeep = 0.f;
;       auto step = [&](const ScanOps& o, int sl) {
;         const f32x4 sA = S0 * o.nkk0 + S1 * o.nkk1;
;         const float sa = red8((sA[0] + sA[1]) + (sA[2] + sA[3]));
;         S0 = S0 * o.w0 + (o.kka0 * sa + o.kd0 * o.v);
;         S1 = S1 * o.w1 + (o.kka1 * sa + o.kd1 * o.v);
;         const f32x4 yA = S0 * o.r0 + S1 * o.r1;
;         const float y = red8((yA[0] + yA[1]) + (yA[2] + yA[3]));
;         ykeep = (cg == (sl & 7)) ? y : ykeep;
;       };
;       ScanOps oa, ob;
;       ldops(oa, 0);
; #pragma unroll
;       for (int s8 = 0; s8 < 32; s8 += 8) {
; #pragma unroll
;         for (int q = 0; q < 8; q += 2) {
;           ldops(ob, s8 + q + 1);
;           step(oa, s8 + q);
;           ldops(oa, (s8 + q + 2) & 31);
;           step(ob, s8 + q + 1);
;         }
;         yw[s8 * 32] = ykeep;
;       }
	v_pk_fma_f32 v[4:5], v[68:69], v[112:113], v[4:5] op_sel_hi:[1,0,1]
	v_pk_fma_f32 v[6:7], v[70:71], v[112:113], v[6:7] op_sel_hi:[1,0,1]
	v_pk_mul_f32 v[98:99], v[0:1], v[80:81]
	v_pk_mul_f32 v[100:101], v[2:3], v[82:83]
	v_pk_fma_f32 v[98:99], v[4:5], v[84:85], v[98:99]
	v_pk_fma_f32 v[100:101], v[6:7], v[86:87], v[100:101]
	v_pk_add_f32 v[98:99], v[98:99], v[100:101]
	v_add_f32_e32 v127, v98, v99
	v_add_f32_dpp v120, v120, v120 row_half_mirror row_mask:0xf bank_mask:0x5 bound_ctrl:1
	v_add_f32_dpp v120, v124, v124 row_half_mirror row_mask:0xf bank_mask:0xa bound_ctrl:1
	v_add_f32_dpp v121, v121, v121 row_half_mirror row_mask:0xf bank_mask:0x5 bound_ctrl:1
	v_add_f32_dpp v121, v125, v125 row_half_mirror row_mask:0xf bank_mask:0xa bound_ctrl:1
	v_add_f32_dpp v122, v122, v122 row_half_mirror row_mask:0xf bank_mask:0x5 bound_ctrl:1
	v_add_f32_dpp v122, v126, v126 row_half_mirror row_mask:0xf bank_mask:0xa bound_ctrl:1
	v_add_f32_dpp v123, v123, v123 row_half_mirror row_mask:0xf bank_mask:0x5 bound_ctrl:1
	v_add_f32_dpp v123, v127, v127 row_half_mirror row_mask:0xf bank_mask:0xa bound_ctrl:1
	v_add_f32_dpp v120, v120, v120 quad_perm:[2,3,0,1] row_mask:0xf bank_mask:0xf bound_ctrl:1
	v_add_f32_dpp v121, v121, v121 quad_perm:[2,3,0,1] row_mask:0xf bank_mask:0xf bound_ctrl:1
	v_add_f32_dpp v122, v122, v122 quad_perm:[2,3,0,1] row_mask:0xf bank_mask:0xf bound_ctrl:1
	v_add_f32_dpp v123, v123, v123 quad_perm:[2,3,0,1] row_mask:0xf bank_mask:0xf bound_ctrl:1
	v_cndmask_b32_e64 v124, v122, v120, s[62:63]
	v_cndmask_b32_e64 v125, v123, v121, s[62:63]
	s_nop 0
	v_add_f32_dpp v124, v124, v124 quad_perm:[1,0,3,2] row_mask:0xf bank_mask:0xf bound_ctrl:1
	v_add_f32_dpp v125, v125, v125 quad_perm:[1,0,3,2] row_mask:0xf bank_mask:0xf bound_ctrl:1
	v_cndmask_b32_e64 v126, v125, v124, s[64:65]
	ds_write_b32 v119, v126 offset:1024
	s_waitcnt lgkmcnt(1)
	ds_read_b128 v[48:51], v117 offset:26112
	ds_read_b128 v[52:55], v117 offset:26128
	ds_read_b128 v[56:59], v117 offset:26368
	ds_read_b128 v[60:63], v117 offset:26384
	ds_read_b128 v[64:67], v117 offset:26624
	ds_read_b128 v[68:71], v117 offset:26640
	ds_read_b128 v[72:75], v117 offset:26880
	ds_read_b128 v[76:79], v117 offset:26896
	ds_read_b128 v[80:83], v117 offset:27136
	ds_read_b128 v[84:87], v117 offset:27152
	v_pk_mul_f32 v[92:93], v[0:1], v[8:9]
	v_pk_mul_f32 v[94:95], v[2:3], v[10:11]
	v_pk_fma_f32 v[92:93], v[4:5], v[12:13], v[92:93]
	v_pk_fma_f32 v[94:95], v[6:7], v[14:15], v[94:95]
	v_pk_mul_f32 v[102:103], v[32:33], v[88:89] op_sel_hi:[1,0]
	v_pk_add_f32 v[92:93], v[92:93], v[94:95]
	v_pk_mul_f32 v[104:105], v[34:35], v[88:89] op_sel_hi:[1,0]
	v_add_f32_e32 v110, v92, v93
	v_pk_mul_f32 v[106:107], v[36:37], v[88:89] op_sel_hi:[1,0]
	v_pk_mul_f32 v[108:109], v[38:39], v[88:89] op_sel_hi:[1,0]
	v_add_f32_dpp v110, v110, v110 quad_perm:[1,0,3,2] row_mask:0xf bank_mask:0xf bound_ctrl:1
	v_pk_fma_f32 v[0:1], v[0:1], v[16:17], v[102:103]
	v_pk_fma_f32 v[2:3], v[2:3], v[18:19], v[104:105]
	v_add_f32_dpp v110, v110, v110 quad_perm:[2,3,0,1] row_mask:0xf bank_mask:0xf bound_ctrl:1
	v_pk_fma_f32 v[4:5], v[4:5], v[20:21], v[106:107]
	v_pk_fma_f32 v[6:7], v[6:7], v[22:23], v[108:109]
	v_add_f32_dpp v112, v110, v110 row_half_mirror row_mask:0xf bank_mask:0xf bound_ctrl:1
	v_pk_fma_f32 v[0:1], v[24:25], v[112:113], v[0:1] op_sel_hi:[1,0,1]
	v_pk_fma_f32 v[2:3], v[26:27], v[112:113], v[2:3] op_sel_hi:[1,0,1]
	v_pk_fma_f32 v[4:5], v[28:29], v[112:113], v[4:5] op_sel_hi:[1,0,1]
	v_pk_fma_f32 v[6:7], v[30:31], v[112:113], v[6:7] op_sel_hi:[1,0,1]
	v_pk_mul_f32 v[98:99], v[0:1], v[40:41]
	v_pk_mul_f32 v[100:101], v[2:3], v[42:43]
	v_pk_fma_f32 v[98:99], v[4:5], v[44:45], v[98:99]
	v_pk_fma_f32 v[100:101], v[6:7], v[46:47], v[100:101]
	v_pk_add_f32 v[98:99], v[98:99], v[100:101]
	v_add_f32_e32 v120, v98, v99
	s_waitcnt lgkmcnt(0)
	ds_read_b128 v[8:11], v117 offset:27648
	ds_read_b128 v[12:15], v117 offset:27664
	ds_read_b128 v[16:19], v117 offset:27904
	ds_read_b128 v[20:23], v117 offset:27920
	ds_read_b128 v[24:27], v117 offset:28160
	ds_read_b128 v[28:31], v117 offset:28176
	ds_read_b128 v[32:35], v117 offset:28416
	ds_read_b128 v[36:39], v117 offset:28432
	ds_read_b128 v[40:43], v117 offset:28672
	ds_read_b128 v[44:47], v117 offset:28688
	ds_read2st64_b32 v[90:91], v118 offset0:113 offset1:119
	v_pk_mul_f32 v[92:93], v[0:1], v[48:49]
	v_pk_mul_f32 v[94:95], v[2:3], v[50:51]
	v_pk_fma_f32 v[92:93], v[4:5], v[52:53], v[92:93]
	v_pk_fma_f32 v[94:95], v[6:7], v[54:55], v[94:95]
	v_pk_mul_f32 v[102:103], v[72:73], v[88:89] op_sel:[0,1] op_sel_hi:[1,1]
	v_pk_add_f32 v[92:93], v[92:93], v[94:95]
	v_pk_mul_f32 v[104:105], v[74:75], v[88:89] op_sel:[0,1] op_sel_hi:[1,1]
	v_add_f32_e32 v110, v92, v93
	v_pk_mul_f32 v[106:107], v[76:77], v[88:89] op_sel:[0,1] op_sel_hi:[1,1]
	v_pk_mul_f32 v[108:109], v[78:79], v[88:89] op_sel:[0,1] op_sel_hi:[1,1]
	v_add_f32_dpp v110, v110, v110 quad_perm:[1,0,3,2] row_mask:0xf bank_mask:0xf bound_ctrl:1
	v_pk_fma_f32 v[0:1], v[0:1], v[56:57], v[102:103]
	v_pk_fma_f32 v[2:3], v[2:3], v[58:59], v[104:105]
	v_add_f32_dpp v110, v110, v110 quad_perm:[2,3,0,1] row_mask:0xf bank_mask:0xf bound_ctrl:1
	v_pk_fma_f32 v[4:5], v[4:5], v[60:61], v[106:107]
	v_pk_fma_f32 v[6:7], v[6:7], v[62:63], v[108:109]
	v_add_f32_dpp v112, v110, v110 row_half_mirror row_mask:0xf bank_mask:0xf bound_ctrl:1
	v_pk_fma_f32 v[0:1], v[64:65], v[112:113], v[0:1] op_sel_hi:[1,0,1]
	v_pk_fma_f32 v[2:3], v[66:67], v[112:113], v[2:3] op_sel_hi:[1,0,1]
	v_pk_fma_f32 v[4:5], v[68:69], v[112:113], v[4:5] op_sel_hi:[1,0,1]
	v_pk_fma_f32 v[6:7], v[70:71], v[112:113], v[6:7] op_sel_hi:[1,0,1]
	v_pk_mul_f32 v[98:99], v[0:1], v[80:81]
	v_pk_mul_f32 v[100:101], v[2:3], v[82:83]
	v_pk_fma_f32 v[98:99], v[4:5], v[84:85], v[98:99]
	v_pk_fma_f32 v[100:101], v[6:7], v[86:87], v[100:101]
	v_pk_add_f32 v[98:99], v[98:99], v[100:101]
	v_add_f32_e32 v121, v98, v99
	s_waitcnt lgkmcnt(0)
; DEV void scan_tile(const Params& p, int l, int tile, char* smem) {
;     ...
;       auto ldops = [&](ScanOps& o, int sl) {
;         const f32x4* b4 = (const f32x4*)(cb + sl * 384);
;         o.nkk0 = b4[cg * 2]; o.nkk1 = b4[cg * 2 + 1];
;         o.w0 = b4[16 + cg * 2]; o.w1 = b4[16 + cg * 2 + 1];
;         o.kka0 = b4[32 + cg * 2]; o.kka1 = b4[32 + cg * 2 + 1];
;         o.kd0 = b4[48 + cg * 2]; o.kd1 = b4[48 + cg * 2 + 1];
;         o.r0 = b4[64 + cg * 2]; o.r1 = b4[64 + cg * 2 + 1];
;         o.v = cb[sl * 384 + vo];
;       };
;       float ykeep = 0.f;
;       auto step = [&](const ScanOps& o, int sl) {
;         const f32x4 sA = S0 * o.nkk0 + S1 * o.nkk1;
;         const float sa = red8((sA[0] + sA[1]) + (sA[2] + sA[3]));
;         S0 = S0 * o.w0 + (o.kka0 * sa + o.kd0 * o.v);
;         S1 = S1 * o.w1 + (o.kka1 * sa + o.kd1 * o.v);
;         const f32x4 yA = S0 * o.r0 + S1 * o.r1;
;         const float y = red8((yA[0] + yA[1]) + (yA[2] + yA[3]));
;         ykeep = (cg == (sl & 7)) ? y : ykeep;
;       };
;       ScanOps oa, ob;
;       ldops(oa, 0);
; #pragma unroll
;       for (int s8 = 0; s8 < 32; s8 += 8) {
; #pragma unroll
;         for (int q = 0; q < 8; q += 2) {
;           ldops(ob, s8 + q + 1);
;           step(oa, s8 + q);
;           ldops(oa, (s8 + q + 2) & 31);
;           step(ob, s8 + q + 1);
;         }
;         yw[s8 * 32] = ykeep;
;       }
	ds_read_b128 v[48:51], v117 offset:29184
	ds_read_b128 v[52:55], v117 offset:29200
	ds_read_b128 v[56:59], v117 offset:29440
	ds_read_b128 v[60:63], v117 offset:29456
	ds_read_b128 v[64:67], v117 offset:29696
	ds_read_b128 v[68:71], v117 offset:29712
	ds_read_b128 v[72:75], v117 offset:29952
	ds_read_b128 v[76:79], v117 offset:29968
	ds_read_b128 v[80:83], v117 offset:30208
	ds_read_b128 v[84:87], v117 offset:30224
	v_pk_mul_f32 v[92:93], v[0:1], v[8:9]
	v_pk_mul_f32 v[94:95], v[2:3], v[10:11]
	v_pk_fma_f32 v[92:93], v[4:5], v[12:13], v[92:93]
	v_pk_fma_f32 v[94:95], v[6:7], v[14:15], v[94:95]
	v_pk_mul_f32 v[102:103], v[32:33], v[90:91] op_sel_hi:[1,0]
	v_pk_add_f32 v[92:93], v[92:93], v[94:95]
	v_pk_mul_f32 v[104:105], v[34:35], v[90:91] op_sel_hi:[1,0]
	v_add_f32_e32 v110, v92, v93
	v_pk_mul_f32 v[106:107], v[36:37], v[90:91] op_sel_hi:[1,0]
	v_pk_mul_f32 v[108:109], v[38:39], v[90:91] op_sel_hi:[1,0]
	v_add_f32_dpp v110, v110, v110 quad_perm:[1,0,3,2] row_mask:0xf bank_mask:0xf bound_ctrl:1
	v_pk_fma_f32 v[0:1], v[0:1], v[16:17], v[102:103]
	v_pk_fma_f32 v[2:3], v[2:3], v[18:19], v[104:105]
	v_add_f32_dpp v110, v110, v110 quad_perm:[2,3,0,1] row_mask:0xf bank_mask:0xf bound_ctrl:1
	v_pk_fma_f32 v[4:5], v[4:5], v[20:21], v[106:107]
	v_pk_fma_f32 v[6:7], v[6:7], v[22:23], v[108:109]
	v_add_f32_dpp v112, v110, v110 row_half_mirror row_mask:0xf bank_mask:0xf bound_ctrl:1
	v_pk_fma_f32 v[0:1], v[24:25], v[112:113], v[0:1] op_sel_hi:[1,0,1]
	v_pk_fma_f32 v[2:3], v[26:27], v[112:113], v[2:3] op_sel_hi:[1,0,1]
	v_pk_fma_f32 v[4:5], v[28:29], v[112:113], v[4:5] op_sel_hi:[1,0,1]
	v_pk_fma_f32 v[6:7], v[30:31], v[112:113], v[6:7] op_sel_hi:[1,0,1]
	v_pk_mul_f32 v[98:99], v[0:1], v[40:41]
	v_pk_mul_f32 v[100:101], v[2:3], v[42:43]
	v_pk_fma_f32 v[98:99], v[4:5], v[44:45], v[98:99]
	v_pk_fma_f32 v[100:101], v[6:7], v[46:47], v[100:101]
	v_pk_add_f32 v[98:99], v[98:99], v[100:101]
	v_add_f32_e32 v122, v98, v99
	s_waitcnt lgkmcnt(0)
	ds_read_b128 v[8:11], v117 offset:30720
	ds_read_b128 v[12:15], v117 offset:30736
	ds_read_b128 v[16:19], v117 offset:30976
	ds_read_b128 v[20:23], v117 offset:30992
	ds_read_b128 v[24:27], v117 offset:31232
	ds_read_b128 v[28:31], v117 offset:31248
	ds_read_b128 v[32:35], v117 offset:31488
	ds_read_b128 v[36:39], v117 offset:31504
	ds_read_b128 v[40:43], v117 offset:31744
	ds_read_b128 v[44:47], v117 offset:31760
	ds_read2st64_b32 v[88:89], v118 offset0:125 offset1:131
	v_pk_mul_f32 v[92:93], v[0:1], v[48:49]
	v_pk_mul_f32 v[94:95], v[2:3], v[50:51]
	v_pk_fma_f32 v[92:93], v[4:5], v[52:53], v[92:93]
	v_pk_fma_f32 v[94:95], v[6:7], v[54:55], v[94:95]
	v_pk_mul_f32 v[102:103], v[72:73], v[90:91] op_sel:[0,1] op_sel_hi:[1,1]
	v_pk_add_f32 v[92:93], v[92:93], v[94:95]
	v_pk_mul_f32 v[104:105], v[74:75], v[90:91] op_sel:[0,1] op_sel_hi:[1,1]
	v_add_f32_e32 v110, v92, v93
	v_pk_mul_f32 v[106:107], v[76:77], v[90:91] op_sel:[0,1] op_sel_hi:[1,1]
	v_pk_mul_f32 v[108:109], v[78:79], v[90:91] op_sel:[0,1] op_sel_hi:[1,1]
	v_add_f32_dpp v110, v110, v110 quad_perm:[1,0,3,2] row_mask:0xf bank_mask:0xf bound_ctrl:1
	v_pk_fma_f32 v[0:1], v[0:1], v[56:57], v[102:103]
	v_pk_fma_f32 v[2:3], v[2:3], v[58:59], v[104:105]
	v_add_f32_dpp v110, v110, v110 quad_perm:[2,3,0,1] row_mask:0xf bank_mask:0xf bound_ctrl:1
	v_pk_fma_f32 v[4:5], v[4:5], v[60:61], v[106:107]
	v_pk_fma_f32 v[6:7], v[6:7], v[62:63], v[108:109]
	v_add_f32_dpp v112, v110, v110 row_half_mirror row_mask:0xf bank_mask:0xf bound_ctrl:1
	v_pk_fma_f32 v[0:1], v[64:65], v[112:113], v[0:1] op_sel_hi:[1,0,1]
	v_pk_fma_f32 v[2:3], v[66:67], v[112:113], v[2:3] op_sel_hi:[1,0,1]
	v_pk_fma_f32 v[4:5], v[68:69], v[112:113], v[4:5] op_sel_hi:[1,0,1]
	v_pk_fma_f32 v[6:7], v[70:71], v[112:113], v[6:7] op_sel_hi:[1,0,1]
	v_pk_mul_f32 v[98:99], v[0:1], v[80:81]
	v_pk_mul_f32 v[100:101], v[2:3], v[82:83]
	v_pk_fma_f32 v[98:99], v[4:5], v[84:85], v[98:99]
	v_pk_fma_f32 v[100:101], v[6:7], v[86:87], v[100:101]
	v_pk_add_f32 v[98:99], v[98:99], v[100:101]
	v_add_f32_e32 v123, v98, v99
	s_waitcnt lgkmcnt(0)
	ds_read_b128 v[48:51], v117 offset:32256
	ds_read_b128 v[52:55], v117 offset:32272
	ds_read_b128 v[56:59], v117 offset:32512
	ds_read_b128 v[60:63], v117 offset:32528
	ds_read_b128 v[64:67], v117 offset:32768
	ds_read_b128 v[68:71], v117 offset:32784
	ds_read_b128 v[72:75], v117 offset:33024
	ds_read_b128 v[76:79], v117 offset:33040
	ds_read_b128 v[80:83], v117 offset:33280
	ds_read_b128 v[84:87], v117 offset:33296
	v_pk_mul_f32 v[92:93], v[0:1], v[8:9]
	v_pk_mul_f32 v[94:95], v[2:3], v[10:11]
	v_pk_fma_f32 v[92:93], v[4:5], v[12:13], v[92:93]
	v_pk_fma_f32 v[94:95], v[6:7], v[14:15], v[94:95]
	v_pk_mul_f32 v[102:103], v[32:33], v[88:89] op_sel_hi:[1,0]
	v_pk_add_f32 v[92:93], v[92:93], v[94:95]
	v_pk_mul_f32 v[104:105], v[34:35], v[88:89] op_sel_hi:[1,0]
	v_add_f32_e32 v110, v92, v93
	v_pk_mul_f32 v[106:107], v[36:37], v[88:89] op_sel_hi:[1,0]
	v_pk_mul_f32 v[108:109], v[38:39], v[88:89] op_sel_hi:[1,0]
	v_add_f32_dpp v110, v110, v110 quad_perm:[1,0,3,2] row_mask:0xf bank_mask:0xf bound_ctrl:1
	v_pk_fma_f32 v[0:1], v[0:1], v[16:17], v[102:103]
	v_pk_fma_f32 v[2:3], v[2:3], v[18:19], v[104:105]
	v_add_f32_dpp v110, v110, v110 quad_perm:[2,3,0,1] row_mask:0xf bank_mask:0xf bound_ctrl:1
	v_pk_fma_f32 v[4:5], v[4:5], v[20:21], v[106:107]
	v_pk_fma_f32 v[6:7], v[6:7], v[22:23], v[108:109]
	v_add_f32_dpp v112, v110, v110 row_half_mirror row_mask:0xf bank_mask:0xf bound_ctrl:1
	v_pk_fma_f32 v[0:1], v[24:25], v[112:113], v[0:1] op_sel_hi:[1,0,1]
	v_pk_fma_f32 v[2:3], v[26:27], v[112:113], v[2:3] op_sel_hi:[1,0,1]
	v_pk_fma_f32 v[4:5], v[28:29], v[112:113], v[4:5] op_sel_hi:[1,0,1]
	v_pk_fma_f32 v[6:7], v[30:31], v[112:113], v[6:7] op_sel_hi:[1,0,1]
	v_pk_mul_f32 v[98:99], v[0:1], v[40:41]
	v_pk_mul_f32 v[100:101], v[2:3], v[42:43]
	v_pk_fma_f32 v[98:99], v[4:5], v[44:45], v[98:99]
	v_pk_fma_f32 v[100:101], v[6:7], v[46:47], v[100:101]
	v_pk_add_f32 v[98:99], v[98:99], v[100:101]
	v_add_f32_e32 v124, v98, v99
	s_waitcnt lgkmcnt(0)
; DEV void scan_tile(const Params& p, int l, int tile, char* smem) {
;     ...
;       auto ldops = [&](ScanOps& o, int sl) {
;         const f32x4* b4 = (const f32x4*)(cb + sl * 384);
;         o.nkk0 = b4[cg * 2]; o.nkk1 = b4[cg * 2 + 1];
;         o.w0 = b4[16 + cg * 2]; o.w1 = b4[16 + cg * 2 + 1];
;         o.kka0 = b4[32 + cg * 2]; o.kka1 = b4[32 + cg * 2 + 1];
;         o.kd0 = b4[48 + cg * 2]; o.kd1 = b4[48 + cg * 2 + 1];
;         o.r0 = b4[64 + cg * 2]; o.r1 = b4[64 + cg * 2 + 1];
;         o.v = cb[sl * 384 + vo];
;       };
;       float ykeep = 0.f;
;       auto step = [&](const ScanOps& o, int sl) {
;         const f32x4 sA = S0 * o.nkk0 + S1 * o.nkk1;
;         const float sa = red8((sA[0] + sA[1]) + (sA[2] + sA[3]));
;         S0 = S0 * o.w0 + (o.kka0 * sa + o.kd0 * o.v);
;         S1 = S1 * o.w1 + (o.kka1 * sa + o.kd1 * o.v);
;         const f32x4 yA = S0 * o.r0 + S1 * o.r1;
;         const float y = red8((yA[0] + yA[1]) + (yA[2] + yA[3]));
;         ykeep = (cg == (sl & 7)) ? y : ykeep;
;       };
;       ScanOps oa, ob;
;       ldops(oa, 0);
; #pragma unroll
;       for (int s8 = 0; s8 < 32; s8 += 8) {
; #pragma unroll
;         for (int q = 0; q < 8; q += 2) {
;           ldops(ob, s8 + q + 1);
;           step(oa, s8 + q);
;           ldops(oa, (s8 + q + 2) & 31);
;           step(ob, s8 + q + 1);
;         }
;         yw[s8 * 32] = ykeep;
;       }
	ds_read_b128 v[8:11], v117 offset:33792
	ds_read_b128 v[12:15], v117 offset:33808
	ds_read_b128 v[16:19], v117 offset:34048
	ds_read_b128 v[20:23], v117 offset:34064
	ds_read_b128 v[24:27], v117 offset:34304
	ds_read_b128 v[28:31], v117 offset:34320
	ds_read_b128 v[32:35], v117 offset:34560
	ds_read_b128 v[36:39], v117 offset:34576
	ds_read_b128 v[40:43], v117 offset:34816
	ds_read_b128 v[44:47], v117 offset:34832
	ds_read2st64_b32 v[90:91], v118 offset0:137 offset1:143
	v_pk_mul_f32 v[92:93], v[0:1], v[48:49]
	v_pk_mul_f32 v[94:95], v[2:3], v[50:51]
	v_pk_fma_f32 v[92:93], v[4:5], v[52:53], v[92:93]
	v_pk_fma_f32 v[94:95], v[6:7], v[54:55], v[94:95]
	v_pk_mul_f32 v[102:103], v[72:73], v[88:89] op_sel:[0,1] op_sel_hi:[1,1]
	v_pk_add_f32 v[92:93], v[92:93], v[94:95]
	v_pk_mul_f32 v[104:105], v[74:75], v[88:89] op_sel:[0,1] op_sel_hi:[1,1]
	v_add_f32_e32 v110, v92, v93
	v_pk_mul_f32 v[106:107], v[76:77], v[88:89] op_sel:[0,1] op_sel_hi:[1,1]
	v_pk_mul_f32 v[108:109], v[78:79], v[88:89] op_sel:[0,1] op_sel_hi:[1,1]
	v_add_f32_dpp v110, v110, v110 quad_perm:[1,0,3,2] row_mask:0xf bank_mask:0xf bound_ctrl:1
	v_pk_fma_f32 v[0:1], v[0:1], v[56:57], v[102:103]
	v_pk_fma_f32 v[2:3], v[2:3], v[58:59], v[104:105]
	v_add_f32_dpp v110, v110, v110 quad_perm:[2,3,0,1] row_mask:0xf bank_mask:0xf bound_ctrl:1
	v_pk_fma_f32 v[4:5], v[4:5], v[60:61], v[106:107]
	v_pk_fma_f32 v[6:7], v[6:7], v[62:63], v[108:109]
	v_add_f32_dpp v112, v110, v110 row_half_mirror row_mask:0xf bank_mask:0xf bound_ctrl:1
	v_pk_fma_f32 v[0:1], v[64:65], v[112:113], v[0:1] op_sel_hi:[1,0,1]
	v_pk_fma_f32 v[2:3], v[66:67], v[112:113], v[2:3] op_sel_hi:[1,0,1]
	v_pk_fma_f32 v[4:5], v[68:69], v[112:113], v[4:5] op_sel_hi:[1,0,1]
	v_pk_fma_f32 v[6:7], v[70:71], v[112:113], v[6:7] op_sel_hi:[1,0,1]
	v_pk_mul_f32 v[98:99], v[0:1], v[80:81]
	v_pk_mul_f32 v[100:101], v[2:3], v[82:83]
	v_pk_fma_f32 v[98:99], v[4:5], v[84:85], v[98:99]
	v_pk_fma_f32 v[100:101], v[6:7], v[86:87], v[100:101]
	v_pk_add_f32 v[98:99], v[98:99], v[100:101]
	v_add_f32_e32 v125, v98, v99
	s_waitcnt lgkmcnt(0)
	ds_read_b128 v[48:51], v117 offset:35328
	ds_read_b128 v[52:55], v117 offset:35344
	ds_read_b128 v[56:59], v117 offset:35584
	ds_read_b128 v[60:63], v117 offset:35600
	ds_read_b128 v[64:67], v117 offset:35840
	ds_read_b128 v[68:71], v117 offset:35856
	ds_read_b128 v[72:75], v117 offset:36096
	ds_read_b128 v[76:79], v117 offset:36112
	ds_read_b128 v[80:83], v117 offset:36352
	ds_read_b128 v[84:87], v117 offset:36368
	v_pk_mul_f32 v[92:93], v[0:1], v[8:9]
	v_pk_mul_f32 v[94:95], v[2:3], v[10:11]
	v_pk_fma_f32 v[92:93], v[4:5], v[12:13], v[92:93]
	v_pk_fma_f32 v[94:95], v[6:7], v[14:15], v[94:95]
	v_pk_mul_f32 v[102:103], v[32:33], v[90:91] op_sel_hi:[1,0]
	v_pk_add_f32 v[92:93], v[92:93], v[94:95]
	v_pk_mul_f32 v[104:105], v[34:35], v[90:91] op_sel_hi:[1,0]
	v_add_f32_e32 v110, v92, v93
	v_pk_mul_f32 v[106:107], v[36:37], v[90:91] op_sel_hi:[1,0]
	v_pk_mul_f32 v[108:109], v[38:39], v[90:91] op_sel_hi:[1,0]
	v_add_f32_dpp v110, v110, v110 quad_perm:[1,0,3,2] row_mask:0xf bank_mask:0xf bound_ctrl:1
	v_pk_fma_f32 v[0:1], v[0:1], v[16:17], v[102:103]
	v_pk_fma_f32 v[2:3], v[2:3], v[18:19], v[104:105]
	v_add_f32_dpp v110, v110, v110 quad_perm:[2,3,0,1] row_mask:0xf bank_mask:0xf bound_ctrl:1
	v_pk_fma_f32 v[4:5], v[4:5], v[20:21], v[106:107]
	v_pk_fma_f32 v[6:7], v[6:7], v[22:23], v[108:109]
	v_add_f32_dpp v112, v110, v110 row_half_mirror row_mask:0xf bank_mask:0xf bound_ctrl:1
	v_pk_fma_f32 v[0:1], v[24:25], v[112:113], v[0:1] op_sel_hi:[1,0,1]
	v_pk_fma_f32 v[2:3], v[26:27], v[112:113], v[2:3] op_sel_hi:[1,0,1]
	v_pk_fma_f32 v[4:5], v[28:29], v[112:113], v[4:5] op_sel_hi:[1,0,1]
	v_pk_fma_f32 v[6:7], v[30:31], v[112:113], v[6:7] op_sel_hi:[1,0,1]
	v_pk_mul_f32 v[98:99], v[0:1], v[40:41]
	v_pk_mul_f32 v[100:101], v[2:3], v[42:43]
	v_pk_fma_f32 v[98:99], v[4:5], v[44:45], v[98:99]
	v_pk_fma_f32 v[100:101], v[6:7], v[46:47], v[100:101]
	v_pk_add_f32 v[98:99], v[98:99], v[100:101]
	v_add_f32_e32 v126, v98, v99
	s_waitcnt lgkmcnt(0)
	ds_read_b128 v[8:11], v117 offset:36864
	ds_read_b128 v[12:15], v117 offset:36880
	ds_read_b128 v[16:19], v117 offset:37120
	ds_read_b128 v[20:23], v117 offset:37136
	ds_read_b128 v[24:27], v117 offset:37376
	ds_read_b128 v[28:31], v117 offset:37392
	ds_read_b128 v[32:35], v117 offset:37632
	ds_read_b128 v[36:39], v117 offset:37648
	ds_read_b128 v[40:43], v117 offset:37888
	ds_read_b128 v[44:47], v117 offset:37904
	ds_read2st64_b32 v[88:89], v118 offset0:149 offset1:155
	v_pk_mul_f32 v[92:93], v[0:1], v[48:49]
	v_pk_mul_f32 v[94:95], v[2:3], v[50:51]
	v_pk_fma_f32 v[92:93], v[4:5], v[52:53], v[92:93]
	v_pk_fma_f32 v[94:95], v[6:7], v[54:55], v[94:95]
	v_pk_mul_f32 v[102:103], v[72:73], v[90:91] op_sel:[0,1] op_sel_hi:[1,1]
	v_pk_add_f32 v[92:93], v[92:93], v[94:95]
	v_pk_mul_f32 v[104:105], v[74:75], v[90:91] op_sel:[0,1] op_sel_hi:[1,1]
	v_add_f32_e32 v110, v92, v93
	v_pk_mul_f32 v[106:107], v[76:77], v[90:91] op_sel:[0,1] op_sel_hi:[1,1]
	v_pk_mul_f32 v[108:109], v[78:79], v[90:91] op_sel:[0,1] op_sel_hi:[1,1]
	v_add_f32_dpp v110, v110, v110 quad_perm:[1,0,3,2] row_mask:0xf bank_mask:0xf bound_ctrl:1
	v_pk_fma_f32 v[0:1], v[0:1], v[56:57], v[102:103]
	v_pk_fma_f32 v[2:3], v[2:3], v[58:59], v[104:105]
	v_add_f32_dpp v110, v110, v110 quad_perm:[2,3,0,1] row_mask:0xf bank_mask:0xf bound_ctrl:1
	v_pk_fma_f32 v[4:5], v[4:5], v[60:61], v[106:107]
	v_pk_fma_f32 v[6:7], v[6:7], v[62:63], v[108:109]
	v_add_f32_dpp v112, v110, v110 row_half_mirror row_mask:0xf bank_mask:0xf bound_ctrl:1
	v_pk_fma_f32 v[0:1], v[64:65], v[112:113], v[0:1] op_sel_hi:[1,0,1]
	v_pk_fma_f32 v[2:3], v[66:67], v[112:113], v[2:3] op_sel_hi:[1,0,1]
; DEV void scan_tile(const Params& p, int l, int tile, char* smem) {
;     ...
;       auto ldops = [&](ScanOps& o, int sl) {
;         const f32x4* b4 = (const f32x4*)(cb + sl * 384);
;         o.nkk0 = b4[cg * 2]; o.nkk1 = b4[cg * 2 + 1];
;         o.w0 = b4[16 + cg * 2]; o.w1 = b4[16 + cg * 2 + 1];
;         o.kka0 = b4[32 + cg * 2]; o.kka1 = b4[32 + cg * 2 + 1];
;         o.kd0 = b4[48 + cg * 2]; o.kd1 = b4[48 + cg * 2 + 1];
;         o.r0 = b4[64 + cg * 2]; o.r1 = b4[64 + cg * 2 + 1];
;         o.v = cb[sl * 384 + vo];
;       };
;       float ykeep = 0.f;
;       auto step = [&](const ScanOps& o, int sl) {
;         const f32x4 sA = S0 * o.nkk0 + S1 * o.nkk1;
;         const float sa = red8((sA[0] + sA[1]) + (sA[2] + sA[3]));
;         S0 = S0 * o.w0 + (o.kka0 * sa + o.kd0 * o.v);
;         S1 = S1 * o.w1 + (o.kka1 * sa + o.kd1 * o.v);
;         const f32x4 yA = S0 * o.r0 + S1 * o.r1;
;         const float y = red8((yA[0] + yA[1]) + (yA[2] + yA[3]));
;         ykeep = (cg == (sl & 7)) ? y : ykeep;
;       };
;       ScanOps oa, ob;
;       ldops(oa, 0);
; #pragma unroll
;       for (int s8 = 0; s8 < 32; s8 += 8) {
; #pragma unroll
;         for (int q = 0; q < 8; q += 2) {
;           ldops(ob, s8 + q + 1);
;           step(oa, s8 + q);
;           ldops(oa, (s8 + q + 2) & 31);
;           step(ob, s8 + q + 1);
;         }
;         yw[s8 * 32] = ykeep;
;       }
	v_pk_fma_f32 v[4:5], v[68:69], v[112:113], v[4:5] op_sel_hi:[1,0,1]
	v_pk_fma_f32 v[6:7], v[70:71], v[112:113], v[6:7] op_sel_hi:[1,0,1]
	v_pk_mul_f32 v[98:99], v[0:1], v[80:81]
	v_pk_mul_f32 v[100:101], v[2:3], v[82:83]
	v_pk_fma_f32 v[98:99], v[4:5], v[84:85], v[98:99]
	v_pk_fma_f32 v[100:101], v[6:7], v[86:87], v[100:101]
	v_pk_add_f32 v[98:99], v[98:99], v[100:101]
	v_add_f32_e32 v127, v98, v99
	v_add_f32_dpp v120, v120, v120 row_half_mirror row_mask:0xf bank_mask:0x5 bound_ctrl:1
	v_add_f32_dpp v120, v124, v124 row_half_mirror row_mask:0xf bank_mask:0xa bound_ctrl:1
	v_add_f32_dpp v121, v121, v121 row_half_mirror row_mask:0xf bank_mask:0x5 bound_ctrl:1
	v_add_f32_dpp v121, v125, v125 row_half_mirror row_mask:0xf bank_mask:0xa bound_ctrl:1
	v_add_f32_dpp v122, v122, v122 row_half_mirror row_mask:0xf bank_mask:0x5 bound_ctrl:1
	v_add_f32_dpp v122, v126, v126 row_half_mirror row_mask:0xf bank_mask:0xa bound_ctrl:1
	v_add_f32_dpp v123, v123, v123 row_half_mirror row_mask:0xf bank_mask:0x5 bound_ctrl:1
	v_add_f32_dpp v123, v127, v127 row_half_mirror row_mask:0xf bank_mask:0xa bound_ctrl:1
	v_add_f32_dpp v120, v120, v120 quad_perm:[2,3,0,1] row_mask:0xf bank_mask:0xf bound_ctrl:1
	v_add_f32_dpp v121, v121, v121 quad_perm:[2,3,0,1] row_mask:0xf bank_mask:0xf bound_ctrl:1
	v_add_f32_dpp v122, v122, v122 quad_perm:[2,3,0,1] row_mask:0xf bank_mask:0xf bound_ctrl:1
	v_add_f32_dpp v123, v123, v123 quad_perm:[2,3,0,1] row_mask:0xf bank_mask:0xf bound_ctrl:1
	v_cndmask_b32_e64 v124, v122, v120, s[62:63]
	v_cndmask_b32_e64 v125, v123, v121, s[62:63]
	s_nop 0
	v_add_f32_dpp v124, v124, v124 quad_perm:[1,0,3,2] row_mask:0xf bank_mask:0xf bound_ctrl:1
	v_add_f32_dpp v125, v125, v125 quad_perm:[1,0,3,2] row_mask:0xf bank_mask:0xf bound_ctrl:1
	v_cndmask_b32_e64 v126, v125, v124, s[64:65]
	ds_write_b32 v119, v126 offset:2048
	s_waitcnt lgkmcnt(1)
	ds_read_b128 v[48:51], v117 offset:38400
	ds_read_b128 v[52:55], v117 offset:38416
	ds_read_b128 v[56:59], v117 offset:38656
	ds_read_b128 v[60:63], v117 offset:38672
	ds_read_b128 v[64:67], v117 offset:38912
	ds_read_b128 v[68:71], v117 offset:38928
	ds_read_b128 v[72:75], v117 offset:39168
	ds_read_b128 v[76:79], v117 offset:39184
	ds_read_b128 v[80:83], v117 offset:39424
	ds_read_b128 v[84:87], v117 offset:39440
	v_pk_mul_f32 v[92:93], v[0:1], v[8:9]
	v_pk_mul_f32 v[94:95], v[2:3], v[10:11]
	v_pk_fma_f32 v[92:93], v[4:5], v[12:13], v[92:93]
	v_pk_fma_f32 v[94:95], v[6:7], v[14:15], v[94:95]
	v_pk_mul_f32 v[102:103], v[32:33], v[88:89] op_sel_hi:[1,0]
	v_pk_add_f32 v[92:93], v[92:93], v[94:95]
	v_pk_mul_f32 v[104:105], v[34:35], v[88:89] op_sel_hi:[1,0]
	v_add_f32_e32 v110, v92, v93
	v_pk_mul_f32 v[106:107], v[36:37], v[88:89] op_sel_hi:[1,0]
	v_pk_mul_f32 v[108:109], v[38:39], v[88:89] op_sel_hi:[1,0]
	v_add_f32_dpp v110, v110, v110 quad_perm:[1,0,3,2] row_mask:0xf bank_mask:0xf bound_ctrl:1
	v_pk_fma_f32 v[0:1], v[0:1], v[16:17], v[102:103]
	v_pk_fma_f32 v[2:3], v[2:3], v[18:19], v[104:105]
	v_add_f32_dpp v110, v110, v110 quad_perm:[2,3,0,1] row_mask:0xf bank_mask:0xf bound_ctrl:1
	v_pk_fma_f32 v[4:5], v[4:5], v[20:21], v[106:107]
	v_pk_fma_f32 v[6:7], v[6:7], v[22:23], v[108:109]
	v_add_f32_dpp v112, v110, v110 row_half_mirror row_mask:0xf bank_mask:0xf bound_ctrl:1
	v_pk_fma_f32 v[0:1], v[24:25], v[112:113], v[0:1] op_sel_hi:[1,0,1]
	v_pk_fma_f32 v[2:3], v[26:27], v[112:113], v[2:3] op_sel_hi:[1,0,1]
	v_pk_fma_f32 v[4:5], v[28:29], v[112:113], v[4:5] op_sel_hi:[1,0,1]
	v_pk_fma_f32 v[6:7], v[30:31], v[112:113], v[6:7] op_sel_hi:[1,0,1]
	v_pk_mul_f32 v[98:99], v[0:1], v[40:41]
	v_pk_mul_f32 v[100:101], v[2:3], v[42:43]
	v_pk_fma_f32 v[98:99], v[4:5], v[44:45], v[98:99]
	v_pk_fma_f32 v[100:101], v[6:7], v[46:47], v[100:101]
	v_pk_add_f32 v[98:99], v[98:99], v[100:101]
	v_add_f32_e32 v120, v98, v99
	s_waitcnt lgkmcnt(0)
	ds_read_b128 v[8:11], v117 offset:39936
	ds_read_b128 v[12:15], v117 offset:39952
	ds_read_b128 v[16:19], v117 offset:40192
	ds_read_b128 v[20:23], v117 offset:40208
	ds_read_b128 v[24:27], v117 offset:40448
	ds_read_b128 v[28:31], v117 offset:40464
	ds_read_b128 v[32:35], v117 offset:40704
	ds_read_b128 v[36:39], v117 offset:40720
	ds_read_b128 v[40:43], v117 offset:40960
	ds_read_b128 v[44:47], v117 offset:40976
	ds_read2st64_b32 v[90:91], v118 offset0:161 offset1:167
	v_pk_mul_f32 v[92:93], v[0:1], v[48:49]
	v_pk_mul_f32 v[94:95], v[2:3], v[50:51]
	v_pk_fma_f32 v[92:93], v[4:5], v[52:53], v[92:93]
	v_pk_fma_f32 v[94:95], v[6:7], v[54:55], v[94:95]
	v_pk_mul_f32 v[102:103], v[72:73], v[88:89] op_sel:[0,1] op_sel_hi:[1,1]
	v_pk_add_f32 v[92:93], v[92:93], v[94:95]
	v_pk_mul_f32 v[104:105], v[74:75], v[88:89] op_sel:[0,1] op_sel_hi:[1,1]
	v_add_f32_e32 v110, v92, v93
	v_pk_mul_f32 v[106:107], v[76:77], v[88:89] op_sel:[0,1] op_sel_hi:[1,1]
	v_pk_mul_f32 v[108:109], v[78:79], v[88:89] op_sel:[0,1] op_sel_hi:[1,1]
	v_add_f32_dpp v110, v110, v110 quad_perm:[1,0,3,2] row_mask:0xf bank_mask:0xf bound_ctrl:1
	v_pk_fma_f32 v[0:1], v[0:1], v[56:57], v[102:103]
	v_pk_fma_f32 v[2:3], v[2:3], v[58:59], v[104:105]
	v_add_f32_dpp v110, v110, v110 quad_perm:[2,3,0,1] row_mask:0xf bank_mask:0xf bound_ctrl:1
	v_pk_fma_f32 v[4:5], v[4:5], v[60:61], v[106:107]
	v_pk_fma_f32 v[6:7], v[6:7], v[62:63], v[108:109]
	v_add_f32_dpp v112, v110, v110 row_half_mirror row_mask:0xf bank_mask:0xf bound_ctrl:1
	v_pk_fma_f32 v[0:1], v[64:65], v[112:113], v[0:1] op_sel_hi:[1,0,1]
	v_pk_fma_f32 v[2:3], v[66:67], v[112:113], v[2:3] op_sel_hi:[1,0,1]
	v_pk_fma_f32 v[4:5], v[68:69], v[112:113], v[4:5] op_sel_hi:[1,0,1]
	v_pk_fma_f32 v[6:7], v[70:71], v[112:113], v[6:7] op_sel_hi:[1,0,1]
	v_pk_mul_f32 v[98:99], v[0:1], v[80:81]
	v_pk_mul_f32 v[100:101], v[2:3], v[82:83]
	v_pk_fma_f32 v[98:99], v[4:5], v[84:85], v[98:99]
	v_pk_fma_f32 v[100:101], v[6:7], v[86:87], v[100:101]
	v_pk_add_f32 v[98:99], v[98:99], v[100:101]
	v_add_f32_e32 v121, v98, v99
	s_waitcnt lgkmcnt(0)
; DEV void scan_tile(const Params& p, int l, int tile, char* smem) {
;     ...
;       auto ldops = [&](ScanOps& o, int sl) {
;         const f32x4* b4 = (const f32x4*)(cb + sl * 384);
;         o.nkk0 = b4[cg * 2]; o.nkk1 = b4[cg * 2 + 1];
;         o.w0 = b4[16 + cg * 2]; o.w1 = b4[16 + cg * 2 + 1];
;         o.kka0 = b4[32 + cg * 2]; o.kka1 = b4[32 + cg * 2 + 1];
;         o.kd0 = b4[48 + cg * 2]; o.kd1 = b4[48 + cg * 2 + 1];
;         o.r0 = b4[64 + cg * 2]; o.r1 = b4[64 + cg * 2 + 1];
;         o.v = cb[sl * 384 + vo];
;       };
;       float ykeep = 0.f;
;       auto step = [&](const ScanOps& o, int sl) {
;         const f32x4 sA = S0 * o.nkk0 + S1 * o.nkk1;
;         const float sa = red8((sA[0] + sA[1]) + (sA[2] + sA[3]));
;         S0 = S0 * o.w0 + (o.kka0 * sa + o.kd0 * o.v);
;         S1 = S1 * o.w1 + (o.kka1 * sa + o.kd1 * o.v);
;         const f32x4 yA = S0 * o.r0 + S1 * o.r1;
;         const float y = red8((yA[0] + yA[1]) + (yA[2] + yA[3]));
;         ykeep = (cg == (sl & 7)) ? y : ykeep;
;       };
;       ScanOps oa, ob;
;       ldops(oa, 0);
; #pragma unroll
;       for (int s8 = 0; s8 < 32; s8 += 8) {
; #pragma unroll
;         for (int q = 0; q < 8; q += 2) {
;           ldops(ob, s8 + q + 1);
;           step(oa, s8 + q);
;           ldops(oa, (s8 + q + 2) & 31);
;           step(ob, s8 + q + 1);
;         }
;         yw[s8 * 32] = ykeep;
;       }
	ds_read_b128 v[48:51], v117 offset:41472
	ds_read_b128 v[52:55], v117 offset:41488
	ds_read_b128 v[56:59], v117 offset:41728
	ds_read_b128 v[60:63], v117 offset:41744
	ds_read_b128 v[64:67], v117 offset:41984
	ds_read_b128 v[68:71], v117 offset:42000
	ds_read_b128 v[72:75], v117 offset:42240
	ds_read_b128 v[76:79], v117 offset:42256
	ds_read_b128 v[80:83], v117 offset:42496
	ds_read_b128 v[84:87], v117 offset:42512
	v_pk_mul_f32 v[92:93], v[0:1], v[8:9]
	v_pk_mul_f32 v[94:95], v[2:3], v[10:11]
	v_pk_fma_f32 v[92:93], v[4:5], v[12:13], v[92:93]
	v_pk_fma_f32 v[94:95], v[6:7], v[14:15], v[94:95]
	v_pk_mul_f32 v[102:103], v[32:33], v[90:91] op_sel_hi:[1,0]
	v_pk_add_f32 v[92:93], v[92:93], v[94:95]
	v_pk_mul_f32 v[104:105], v[34:35], v[90:91] op_sel_hi:[1,0]
	v_add_f32_e32 v110, v92, v93
	v_pk_mul_f32 v[106:107], v[36:37], v[90:91] op_sel_hi:[1,0]
	v_pk_mul_f32 v[108:109], v[38:39], v[90:91] op_sel_hi:[1,0]
	v_add_f32_dpp v110, v110, v110 quad_perm:[1,0,3,2] row_mask:0xf bank_mask:0xf bound_ctrl:1
	v_pk_fma_f32 v[0:1], v[0:1], v[16:17], v[102:103]
	v_pk_fma_f32 v[2:3], v[2:3], v[18:19], v[104:105]
	v_add_f32_dpp v110, v110, v110 quad_perm:[2,3,0,1] row_mask:0xf bank_mask:0xf bound_ctrl:1
	v_pk_fma_f32 v[4:5], v[4:5], v[20:21], v[106:107]
	v_pk_fma_f32 v[6:7], v[6:7], v[22:23], v[108:109]
	v_add_f32_dpp v112, v110, v110 row_half_mirror row_mask:0xf bank_mask:0xf bound_ctrl:1
	v_pk_fma_f32 v[0:1], v[24:25], v[112:113], v[0:1] op_sel_hi:[1,0,1]
	v_pk_fma_f32 v[2:3], v[26:27], v[112:113], v[2:3] op_sel_hi:[1,0,1]
	v_pk_fma_f32 v[4:5], v[28:29], v[112:113], v[4:5] op_sel_hi:[1,0,1]
	v_pk_fma_f32 v[6:7], v[30:31], v[112:113], v[6:7] op_sel_hi:[1,0,1]
	v_pk_mul_f32 v[98:99], v[0:1], v[40:41]
	v_pk_mul_f32 v[100:101], v[2:3], v[42:43]
	v_pk_fma_f32 v[98:99], v[4:5], v[44:45], v[98:99]
	v_pk_fma_f32 v[100:101], v[6:7], v[46:47], v[100:101]
	v_pk_add_f32 v[98:99], v[98:99], v[100:101]
	v_add_f32_e32 v122, v98, v99
	s_waitcnt lgkmcnt(0)
	ds_read_b128 v[8:11], v117 offset:43008
	ds_read_b128 v[12:15], v117 offset:43024
	ds_read_b128 v[16:19], v117 offset:43264
	ds_read_b128 v[20:23], v117 offset:43280
	ds_read_b128 v[24:27], v117 offset:43520
	ds_read_b128 v[28:31], v117 offset:43536
	ds_read_b128 v[32:35], v117 offset:43776
	ds_read_b128 v[36:39], v117 offset:43792
	ds_read_b128 v[40:43], v117 offset:44032
	ds_read_b128 v[44:47], v117 offset:44048
	ds_read2st64_b32 v[88:89], v118 offset0:173 offset1:179
	v_pk_mul_f32 v[92:93], v[0:1], v[48:49]
	v_pk_mul_f32 v[94:95], v[2:3], v[50:51]
	v_pk_fma_f32 v[92:93], v[4:5], v[52:53], v[92:93]
	v_pk_fma_f32 v[94:95], v[6:7], v[54:55], v[94:95]
	v_pk_mul_f32 v[102:103], v[72:73], v[90:91] op_sel:[0,1] op_sel_hi:[1,1]
	v_pk_add_f32 v[92:93], v[92:93], v[94:95]
	v_pk_mul_f32 v[104:105], v[74:75], v[90:91] op_sel:[0,1] op_sel_hi:[1,1]
	v_add_f32_e32 v110, v92, v93
	v_pk_mul_f32 v[106:107], v[76:77], v[90:91] op_sel:[0,1] op_sel_hi:[1,1]
	v_pk_mul_f32 v[108:109], v[78:79], v[90:91] op_sel:[0,1] op_sel_hi:[1,1]
	v_add_f32_dpp v110, v110, v110 quad_perm:[1,0,3,2] row_mask:0xf bank_mask:0xf bound_ctrl:1
	v_pk_fma_f32 v[0:1], v[0:1], v[56:57], v[102:103]
	v_pk_fma_f32 v[2:3], v[2:3], v[58:59], v[104:105]
	v_add_f32_dpp v110, v110, v110 quad_perm:[2,3,0,1] row_mask:0xf bank_mask:0xf bound_ctrl:1
	v_pk_fma_f32 v[4:5], v[4:5], v[60:61], v[106:107]
	v_pk_fma_f32 v[6:7], v[6:7], v[62:63], v[108:109]
	v_add_f32_dpp v112, v110, v110 row_half_mirror row_mask:0xf bank_mask:0xf bound_ctrl:1
	v_pk_fma_f32 v[0:1], v[64:65], v[112:113], v[0:1] op_sel_hi:[1,0,1]
	v_pk_fma_f32 v[2:3], v[66:67], v[112:113], v[2:3] op_sel_hi:[1,0,1]
	v_pk_fma_f32 v[4:5], v[68:69], v[112:113], v[4:5] op_sel_hi:[1,0,1]
	v_pk_fma_f32 v[6:7], v[70:71], v[112:113], v[6:7] op_sel_hi:[1,0,1]
	v_pk_mul_f32 v[98:99], v[0:1], v[80:81]
	v_pk_mul_f32 v[100:101], v[2:3], v[82:83]
	v_pk_fma_f32 v[98:99], v[4:5], v[84:85], v[98:99]
	v_pk_fma_f32 v[100:101], v[6:7], v[86:87], v[100:101]
	v_pk_add_f32 v[98:99], v[98:99], v[100:101]
	v_add_f32_e32 v123, v98, v99
	s_waitcnt lgkmcnt(0)
	ds_read_b128 v[48:51], v117 offset:44544
	ds_read_b128 v[52:55], v117 offset:44560
	ds_read_b128 v[56:59], v117 offset:44800
	ds_read_b128 v[60:63], v117 offset:44816
	ds_read_b128 v[64:67], v117 offset:45056
	ds_read_b128 v[68:71], v117 offset:45072
	ds_read_b128 v[72:75], v117 offset:45312
	ds_read_b128 v[76:79], v117 offset:45328
	ds_read_b128 v[80:83], v117 offset:45568
	ds_read_b128 v[84:87], v117 offset:45584
	v_pk_mul_f32 v[92:93], v[0:1], v[8:9]
	v_pk_mul_f32 v[94:95], v[2:3], v[10:11]
	v_pk_fma_f32 v[92:93], v[4:5], v[12:13], v[92:93]
	v_pk_fma_f32 v[94:95], v[6:7], v[14:15], v[94:95]
	v_pk_mul_f32 v[102:103], v[32:33], v[88:89] op_sel_hi:[1,0]
	v_pk_add_f32 v[92:93], v[92:93], v[94:95]
	v_pk_mul_f32 v[104:105], v[34:35], v[88:89] op_sel_hi:[1,0]
	v_add_f32_e32 v110, v92, v93
	v_pk_mul_f32 v[106:107], v[36:37], v[88:89] op_sel_hi:[1,0]
	v_pk_mul_f32 v[108:109], v[38:39], v[88:89] op_sel_hi:[1,0]
	v_add_f32_dpp v110, v110, v110 quad_perm:[1,0,3,2] row_mask:0xf bank_mask:0xf bound_ctrl:1
	v_pk_fma_f32 v[0:1], v[0:1], v[16:17], v[102:103]
	v_pk_fma_f32 v[2:3], v[2:3], v[18:19], v[104:105]
	v_add_f32_dpp v110, v110, v110 quad_perm:[2,3,0,1] row_mask:0xf bank_mask:0xf bound_ctrl:1
	v_pk_fma_f32 v[4:5], v[4:5], v[20:21], v[106:107]
	v_pk_fma_f32 v[6:7], v[6:7], v[22:23], v[108:109]
	v_add_f32_dpp v112, v110, v110 row_half_mirror row_mask:0xf bank_mask:0xf bound_ctrl:1
	v_pk_fma_f32 v[0:1], v[24:25], v[112:113], v[0:1] op_sel_hi:[1,0,1]
	v_pk_fma_f32 v[2:3], v[26:27], v[112:113], v[2:3] op_sel_hi:[1,0,1]
	v_pk_fma_f32 v[4:5], v[28:29], v[112:113], v[4:5] op_sel_hi:[1,0,1]
	v_pk_fma_f32 v[6:7], v[30:31], v[112:113], v[6:7] op_sel_hi:[1,0,1]
	v_pk_mul_f32 v[98:99], v[0:1], v[40:41]
	v_pk_mul_f32 v[100:101], v[2:3], v[42:43]
	v_pk_fma_f32 v[98:99], v[4:5], v[44:45], v[98:99]
	v_pk_fma_f32 v[100:101], v[6:7], v[46:47], v[100:101]
	v_pk_add_f32 v[98:99], v[98:99], v[100:101]
	v_add_f32_e32 v124, v98, v99
	s_waitcnt lgkmcnt(0)
; DEV void scan_tile(const Params& p, int l, int tile, char* smem) {
;     ...
;       auto ldops = [&](ScanOps& o, int sl) {
;         const f32x4* b4 = (const f32x4*)(cb + sl * 384);
;         o.nkk0 = b4[cg * 2]; o.nkk1 = b4[cg * 2 + 1];
;         o.w0 = b4[16 + cg * 2]; o.w1 = b4[16 + cg * 2 + 1];
;         o.kka0 = b4[32 + cg * 2]; o.kka1 = b4[32 + cg * 2 + 1];
;         o.kd0 = b4[48 + cg * 2]; o.kd1 = b4[48 + cg * 2 + 1];
;         o.r0 = b4[64 + cg * 2]; o.r1 = b4[64 + cg * 2 + 1];
;         o.v = cb[sl * 384 + vo];
;       };
;       float ykeep = 0.f;
;       auto step = [&](const ScanOps& o, int sl) {
;         const f32x4 sA = S0 * o.nkk0 + S1 * o.nkk1;
;         const float sa = red8((sA[0] + sA[1]) + (sA[2] + sA[3]));
;         S0 = S0 * o.w0 + (o.kka0 * sa + o.kd0 * o.v);
;         S1 = S1 * o.w1 + (o.kka1 * sa + o.kd1 * o.v);
;         const f32x4 yA = S0 * o.r0 + S1 * o.r1;
;         const float y = red8((yA[0] + yA[1]) + (yA[2] + yA[3]));
;         ykeep = (cg == (sl & 7)) ? y : ykeep;
;       };
;       ScanOps oa, ob;
;       ldops(oa, 0);
; #pragma unroll
;       for (int s8 = 0; s8 < 32; s8 += 8) {
; #pragma unroll
;         for (int q = 0; q < 8; q += 2) {
;           ldops(ob, s8 + q + 1);
;           step(oa, s8 + q);
;           ldops(oa, (s8 + q + 2) & 31);
;           step(ob, s8 + q + 1);
;         }
;         yw[s8 * 32] = ykeep;
;       }
	ds_read_b128 v[8:11], v117 offset:46080
	ds_read_b128 v[12:15], v117 offset:46096
	ds_read_b128 v[16:19], v117 offset:46336
	ds_read_b128 v[20:23], v117 offset:46352
	ds_read_b128 v[24:27], v117 offset:46592
	ds_read_b128 v[28:31], v117 offset:46608
	ds_read_b128 v[32:35], v117 offset:46848
	ds_read_b128 v[36:39], v117 offset:46864
	ds_read_b128 v[40:43], v117 offset:47104
	ds_read_b128 v[44:47], v117 offset:47120
	ds_read2st64_b32 v[90:91], v118 offset0:185 offset1:191
	v_pk_mul_f32 v[92:93], v[0:1], v[48:49]
	v_pk_mul_f32 v[94:95], v[2:3], v[50:51]
	v_pk_fma_f32 v[92:93], v[4:5], v[52:53], v[92:93]
	v_pk_fma_f32 v[94:95], v[6:7], v[54:55], v[94:95]
	v_pk_mul_f32 v[102:103], v[72:73], v[88:89] op_sel:[0,1] op_sel_hi:[1,1]
	v_pk_add_f32 v[92:93], v[92:93], v[94:95]
	v_pk_mul_f32 v[104:105], v[74:75], v[88:89] op_sel:[0,1] op_sel_hi:[1,1]
	v_add_f32_e32 v110, v92, v93
	v_pk_mul_f32 v[106:107], v[76:77], v[88:89] op_sel:[0,1] op_sel_hi:[1,1]
	v_pk_mul_f32 v[108:109], v[78:79], v[88:89] op_sel:[0,1] op_sel_hi:[1,1]
	v_add_f32_dpp v110, v110, v110 quad_perm:[1,0,3,2] row_mask:0xf bank_mask:0xf bound_ctrl:1
	v_pk_fma_f32 v[0:1], v[0:1], v[56:57], v[102:103]
	v_pk_fma_f32 v[2:3], v[2:3], v[58:59], v[104:105]
	v_add_f32_dpp v110, v110, v110 quad_perm:[2,3,0,1] row_mask:0xf bank_mask:0xf bound_ctrl:1
	v_pk_fma_f32 v[4:5], v[4:5], v[60:61], v[106:107]
	v_pk_fma_f32 v[6:7], v[6:7], v[62:63], v[108:109]
	v_add_f32_dpp v112, v110, v110 row_half_mirror row_mask:0xf bank_mask:0xf bound_ctrl:1
	v_pk_fma_f32 v[0:1], v[64:65], v[112:113], v[0:1] op_sel_hi:[1,0,1]
	v_pk_fma_f32 v[2:3], v[66:67], v[112:113], v[2:3] op_sel_hi:[1,0,1]
	v_pk_fma_f32 v[4:5], v[68:69], v[112:113], v[4:5] op_sel_hi:[1,0,1]
	v_pk_fma_f32 v[6:7], v[70:71], v[112:113], v[6:7] op_sel_hi:[1,0,1]
	v_pk_mul_f32 v[98:99], v[0:1], v[80:81]
	v_pk_mul_f32 v[100:101], v[2:3], v[82:83]
	v_pk_fma_f32 v[98:99], v[4:5], v[84:85], v[98:99]
	v_pk_fma_f32 v[100:101], v[6:7], v[86:87], v[100:101]
	v_pk_add_f32 v[98:99], v[98:99], v[100:101]
	v_add_f32_e32 v125, v98, v99
	s_waitcnt lgkmcnt(0)
	ds_read_b128 v[48:51], v117 offset:47616
	ds_read_b128 v[52:55], v117 offset:47632
	ds_read_b128 v[56:59], v117 offset:47872
	ds_read_b128 v[60:63], v117 offset:47888
	ds_read_b128 v[64:67], v117 offset:48128
	ds_read_b128 v[68:71], v117 offset:48144
	ds_read_b128 v[72:75], v117 offset:48384
	ds_read_b128 v[76:79], v117 offset:48400
	ds_read_b128 v[80:83], v117 offset:48640
	ds_read_b128 v[84:87], v117 offset:48656
	v_pk_mul_f32 v[92:93], v[0:1], v[8:9]
	v_pk_mul_f32 v[94:95], v[2:3], v[10:11]
	v_pk_fma_f32 v[92:93], v[4:5], v[12:13], v[92:93]
	v_pk_fma_f32 v[94:95], v[6:7], v[14:15], v[94:95]
	v_pk_mul_f32 v[102:103], v[32:33], v[90:91] op_sel_hi:[1,0]
	v_pk_add_f32 v[92:93], v[92:93], v[94:95]
	v_pk_mul_f32 v[104:105], v[34:35], v[90:91] op_sel_hi:[1,0]
	v_add_f32_e32 v110, v92, v93
	v_pk_mul_f32 v[106:107], v[36:37], v[90:91] op_sel_hi:[1,0]
	v_pk_mul_f32 v[108:109], v[38:39], v[90:91] op_sel_hi:[1,0]
	v_add_f32_dpp v110, v110, v110 quad_perm:[1,0,3,2] row_mask:0xf bank_mask:0xf bound_ctrl:1
	v_pk_fma_f32 v[0:1], v[0:1], v[16:17], v[102:103]
	v_pk_fma_f32 v[2:3], v[2:3], v[18:19], v[104:105]
	v_add_f32_dpp v110, v110, v110 quad_perm:[2,3,0,1] row_mask:0xf bank_mask:0xf bound_ctrl:1
	v_pk_fma_f32 v[4:5], v[4:5], v[20:21], v[106:107]
	v_pk_fma_f32 v[6:7], v[6:7], v[22:23], v[108:109]
	v_add_f32_dpp v112, v110, v110 row_half_mirror row_mask:0xf bank_mask:0xf bound_ctrl:1
	v_pk_fma_f32 v[0:1], v[24:25], v[112:113], v[0:1] op_sel_hi:[1,0,1]
	v_pk_fma_f32 v[2:3], v[26:27], v[112:113], v[2:3] op_sel_hi:[1,0,1]
	v_pk_fma_f32 v[4:5], v[28:29], v[112:113], v[4:5] op_sel_hi:[1,0,1]
	v_pk_fma_f32 v[6:7], v[30:31], v[112:113], v[6:7] op_sel_hi:[1,0,1]
	v_pk_mul_f32 v[98:99], v[0:1], v[40:41]
	v_pk_mul_f32 v[100:101], v[2:3], v[42:43]
	v_pk_fma_f32 v[98:99], v[4:5], v[44:45], v[98:99]
	v_pk_fma_f32 v[100:101], v[6:7], v[46:47], v[100:101]
	v_pk_add_f32 v[98:99], v[98:99], v[100:101]
	v_add_f32_e32 v126, v98, v99
	s_waitcnt lgkmcnt(0)
; DEV void scan_tile(const Params& p, int l, int tile, char* smem) {
;     ...
;       auto step = [&](const ScanOps& o, int sl) {
;         const f32x4 sA = S0 * o.nkk0 + S1 * o.nkk1;
;         const float sa = red8((sA[0] + sA[1]) + (sA[2] + sA[3]));
;         S0 = S0 * o.w0 + (o.kka0 * sa + o.kd0 * o.v);
;         S1 = S1 * o.w1 + (o.kka1 * sa + o.kd1 * o.v);
;         const f32x4 yA = S0 * o.r0 + S1 * o.r1;
;         const float y = red8((yA[0] + yA[1]) + (yA[2] + yA[3]));
;         ykeep = (cg == (sl & 7)) ? y : ykeep;
;       };
;       ScanOps oa, ob;
;       ldops(oa, 0);
; #pragma unroll
;       for (int s8 = 0; s8 < 32; s8 += 8) {
; #pragma unroll
;         for (int q = 0; q < 8; q += 2) {
;           ldops(ob, s8 + q + 1);
;           step(oa, s8 + q);
;           ldops(oa, (s8 + q + 2) & 31);
;           step(ob, s8 + q + 1);
;         }
;         yw[s8 * 32] = ykeep;
;       }
;     } else {
;       const int pw = w - 4;
;       if (ch > 0) flush(ch - 1, buf ^ 1, tid - 256);
;       if (ch + 1 < 136) produce(ch + 1, buf ^ 1, pw, 4);
;     }
;     __syncthreads();
	v_pk_mul_f32 v[92:93], v[0:1], v[48:49]
	v_pk_mul_f32 v[94:95], v[2:3], v[50:51]
	v_pk_fma_f32 v[92:93], v[4:5], v[52:53], v[92:93]
	v_pk_fma_f32 v[94:95], v[6:7], v[54:55], v[94:95]
	v_pk_mul_f32 v[102:103], v[72:73], v[90:91] op_sel:[0,1] op_sel_hi:[1,1]
	v_pk_add_f32 v[92:93], v[92:93], v[94:95]
	v_pk_mul_f32 v[104:105], v[74:75], v[90:91] op_sel:[0,1] op_sel_hi:[1,1]
	v_add_f32_e32 v110, v92, v93
	v_pk_mul_f32 v[106:107], v[76:77], v[90:91] op_sel:[0,1] op_sel_hi:[1,1]
	v_pk_mul_f32 v[108:109], v[78:79], v[90:91] op_sel:[0,1] op_sel_hi:[1,1]
	v_add_f32_dpp v110, v110, v110 quad_perm:[1,0,3,2] row_mask:0xf bank_mask:0xf bound_ctrl:1
	v_pk_fma_f32 v[0:1], v[0:1], v[56:57], v[102:103]
	v_pk_fma_f32 v[2:3], v[2:3], v[58:59], v[104:105]
	v_add_f32_dpp v110, v110, v110 quad_perm:[2,3,0,1] row_mask:0xf bank_mask:0xf bound_ctrl:1
	v_pk_fma_f32 v[4:5], v[4:5], v[60:61], v[106:107]
	v_pk_fma_f32 v[6:7], v[6:7], v[62:63], v[108:109]
	v_add_f32_dpp v112, v110, v110 row_half_mirror row_mask:0xf bank_mask:0xf bound_ctrl:1
	v_pk_fma_f32 v[0:1], v[64:65], v[112:113], v[0:1] op_sel_hi:[1,0,1]
	v_pk_fma_f32 v[2:3], v[66:67], v[112:113], v[2:3] op_sel_hi:[1,0,1]
	v_pk_fma_f32 v[4:5], v[68:69], v[112:113], v[4:5] op_sel_hi:[1,0,1]
	v_pk_fma_f32 v[6:7], v[70:71], v[112:113], v[6:7] op_sel_hi:[1,0,1]
	v_pk_mul_f32 v[98:99], v[0:1], v[80:81]
	v_pk_mul_f32 v[100:101], v[2:3], v[82:83]
	v_pk_fma_f32 v[98:99], v[4:5], v[84:85], v[98:99]
	v_pk_fma_f32 v[100:101], v[6:7], v[86:87], v[100:101]
	v_pk_add_f32 v[98:99], v[98:99], v[100:101]
	v_add_f32_e32 v127, v98, v99
	v_add_f32_dpp v120, v120, v120 row_half_mirror row_mask:0xf bank_mask:0x5 bound_ctrl:1
	v_add_f32_dpp v120, v124, v124 row_half_mirror row_mask:0xf bank_mask:0xa bound_ctrl:1
	v_add_f32_dpp v121, v121, v121 row_half_mirror row_mask:0xf bank_mask:0x5 bound_ctrl:1
	v_add_f32_dpp v121, v125, v125 row_half_mirror row_mask:0xf bank_mask:0xa bound_ctrl:1
	v_add_f32_dpp v122, v122, v122 row_half_mirror row_mask:0xf bank_mask:0x5 bound_ctrl:1
	v_add_f32_dpp v122, v126, v126 row_half_mirror row_mask:0xf bank_mask:0xa bound_ctrl:1
	v_add_f32_dpp v123, v123, v123 row_half_mirror row_mask:0xf bank_mask:0x5 bound_ctrl:1
	v_add_f32_dpp v123, v127, v127 row_half_mirror row_mask:0xf bank_mask:0xa bound_ctrl:1
	v_add_f32_dpp v120, v120, v120 quad_perm:[2,3,0,1] row_mask:0xf bank_mask:0xf bound_ctrl:1
	v_add_f32_dpp v121, v121, v121 quad_perm:[2,3,0,1] row_mask:0xf bank_mask:0xf bound_ctrl:1
	v_add_f32_dpp v122, v122, v122 quad_perm:[2,3,0,1] row_mask:0xf bank_mask:0xf bound_ctrl:1
	v_add_f32_dpp v123, v123, v123 quad_perm:[2,3,0,1] row_mask:0xf bank_mask:0xf bound_ctrl:1
	v_cndmask_b32_e64 v124, v122, v120, s[62:63]
	v_cndmask_b32_e64 v125, v123, v121, s[62:63]
	s_nop 0
	v_add_f32_dpp v124, v124, v124 quad_perm:[1,0,3,2] row_mask:0xf bank_mask:0xf bound_ctrl:1
	v_add_f32_dpp v125, v125, v125 quad_perm:[1,0,3,2] row_mask:0xf bank_mask:0xf bound_ctrl:1
	v_cndmask_b32_e64 v126, v125, v124, s[64:65]
	ds_write_b32 v119, v126 offset:3072
	v_xor_b32_e32 v117, 0xc000, v117
	v_xor_b32_e32 v118, 0xc000, v118
	v_xor_b32_e32 v119, 0x1000, v119
	s_add_u32 s46, s46, 1
	s_cmp_lt_u32 s46, 136
	s_waitcnt lgkmcnt(0)
	s_barrier
	s_cbranch_scc1 .Lsc_cloop
	s_branch .LBB0_192
